# v6 + s_setprio 1 issued before the barrier that opens each MFMA segment and s_setprio 0 after the barrier that closes it (MFMA burst starts/ends directly at the barrier)
# speedup vs baseline: 1.0278x; 1.0014x over previous
; #define PG8_STAGE(bufoff, gbase, voff) do { _Pragma("unroll") for (int _i = 0; _i < 2; ++_i) \
;         __builtin_amdgcn_global_load_lds((const unsigned*)((const char*)(gbase) + (voff)[_i]), (LAS unsigned*)(lds + (bufoff) + ldsw + _i * 8192), 16, 0, 0); } while (0)
; #define PG8_LDA(dst, b, h) do { _Pragma("unroll") for (int m = 0; m < 4; ++m) _Pragma("unroll") for (int k = 0; k < 2; ++k) dst[m][k] = *(const LAS bf16x8*)(lds + PG8_SA(b, h) + aoff + m * 2048 + k * KOFF); } while (0)
; #define PG8_LDB(dst, b, h) do { _Pragma("unroll") for (int n = 0; n < 2; ++n) _Pragma("unroll") for (int k = 0; k < 2; ++k) dst[n][k] = *(const LAS bf16x8*)(lds + PG8_SB(b, h) + boff + n * 2048 + k * KOFF); } while (0)
; #define PG8_WAIT_V(n) asm volatile("s_waitcnt vmcnt(" #n ")" ::: "memory")
; #define PG8_WAIT_L(n) asm volatile("s_waitcnt lgkmcnt(" #n ")" ::: "memory")
; #define PG8_BAR __builtin_amdgcn_s_barrier()
; #define PG8_SCHED __builtin_amdgcn_sched_barrier(0)
; template <class Epi, bool ALIGN_EPI = true, bool FP8 = false>
; __device__ __forceinline__ void gemm_phase(LAS unsigned char* lds, const Gemm g, const StaticOrder& S, const Epi& E, const int wid) {
;     ...
;             PG8_LDB(B0, 0, 0); PG8_LDB(B1, 0, 1); PG8_SCHED; PG8_LDA(At, 0, 0); PG8_STAGE(PG8_SA(1, 1), a1 + hstep, voffA);
;             PG8_WAIT_V(8); PG8_WAIT_L(0); PG8_BAR; PG8_MMA(0, 0, At, B0); PG8_MMA(0, 1, At, B1); PG8_BAR; PG8_SCHED;
;             PG8_LDA(At, 0, 1); PG8_STAGE(PG8_SB(0, 0), b2, voffB); PG8_STAGE(PG8_SB(0, 1), b2 + hstep, voffB); PG8_STAGE(PG8_SA(0, 0), a2, voffA);
;             PG8_WAIT_V(8); PG8_WAIT_L(0); PG8_BAR; PG8_MMA(1, 0, At, B0); PG8_MMA(1, 1, At, B1); PG8_BAR; PG8_SCHED;
.LBB0_506:
	ds_read_b128 v[146:149], v137
	ds_read_b128 v[154:157], v137 offset:1024
	ds_read_b128 v[158:161], v137 offset:2048
	ds_read_b128 v[162:165], v137 offset:3072
	ds_read_b128 v[166:169], v152
	ds_read_b128 v[170:173], v152 offset:1024
	ds_read_b128 v[174:177], v152 offset:2048
	ds_read_b128 v[178:181], v152 offset:3072
	s_add_i32 s52, s34, 2
	s_add_u32 s35, s30, 0xfff80080
	s_addc_u32 s36, s31, -1
	s_cmp_eq_u32 s39, s34
	s_cselect_b32 s34, s38, s42
	s_cselect_b32 s37, s3, s36
	s_cselect_b32 s36, s23, s35
	s_cselect_b32 s35, s25, s43
	v_lshl_add_u64 v[214:215], s[30:31], 0, v[140:141]
	s_add_i32 m0, s75, 0xc000
	ds_read_b128 v[182:185], v153
	ds_read_b128 v[186:189], v153 offset:1024
	ds_read_b128 v[190:193], v153 offset:2048
	ds_read_b128 v[194:197], v153 offset:3072
	ds_read_b128 v[198:201], v153 offset:4096
	ds_read_b128 v[202:205], v153 offset:5120
	ds_read_b128 v[206:209], v153 offset:6144
	ds_read_b128 v[210:213], v153 offset:7168
	global_load_lds_dwordx4 v[214:215], off
	v_lshl_add_u64 v[214:215], s[30:31], 0, v[142:143]
	s_add_i32 m0, s75, 0xe000
	s_nop 0
	global_load_lds_dwordx4 v[214:215], off
	s_waitcnt vmcnt(8)
	s_waitcnt lgkmcnt(0)
	s_setprio 1
	s_barrier
	v_mfma_f32_16x16x32_bf16 v[124:127], v[146:149], v[182:185], v[124:127]
	v_mfma_f32_16x16x32_bf16 v[120:123], v[158:161], v[182:185], v[120:123]
	v_mfma_f32_16x16x32_bf16 v[108:111], v[146:149], v[190:193], v[108:111]
	v_mfma_f32_16x16x32_bf16 v[104:107], v[158:161], v[190:193], v[104:107]
	v_mfma_f32_16x16x32_bf16 v[92:95], v[146:149], v[198:201], v[92:95]
	v_mfma_f32_16x16x32_bf16 v[88:91], v[158:161], v[198:201], v[88:91]
	v_mfma_f32_16x16x32_bf16 v[76:79], v[146:149], v[206:209], v[76:79]
	v_mfma_f32_16x16x32_bf16 v[72:75], v[158:161], v[206:209], v[72:75]
	v_mfma_f32_16x16x32_bf16 v[124:127], v[154:157], v[186:189], v[124:127]
	v_mfma_f32_16x16x32_bf16 v[120:123], v[162:165], v[186:189], v[120:123]
	v_mfma_f32_16x16x32_bf16 v[108:111], v[154:157], v[194:197], v[108:111]
	v_mfma_f32_16x16x32_bf16 v[104:107], v[162:165], v[194:197], v[104:107]
	v_mfma_f32_16x16x32_bf16 v[92:95], v[154:157], v[202:205], v[92:95]
	v_mfma_f32_16x16x32_bf16 v[88:91], v[162:165], v[202:205], v[88:91]
	v_mfma_f32_16x16x32_bf16 v[76:79], v[154:157], v[210:213], v[76:79]
	v_mfma_f32_16x16x32_bf16 v[72:75], v[162:165], v[210:213], v[72:75]
	v_mfma_f32_16x16x32_bf16 v[116:119], v[166:169], v[182:185], v[116:119]
	v_mfma_f32_16x16x32_bf16 v[112:115], v[174:177], v[182:185], v[112:115]
	v_mfma_f32_16x16x32_bf16 v[100:103], v[166:169], v[190:193], v[100:103]
	v_mfma_f32_16x16x32_bf16 v[96:99], v[174:177], v[190:193], v[96:99]
	v_mfma_f32_16x16x32_bf16 v[84:87], v[166:169], v[198:201], v[84:87]
	v_mfma_f32_16x16x32_bf16 v[80:83], v[174:177], v[198:201], v[80:83]
	v_mfma_f32_16x16x32_bf16 v[68:71], v[166:169], v[206:209], v[68:71]
	v_mfma_f32_16x16x32_bf16 v[64:67], v[174:177], v[206:209], v[64:67]
	v_mfma_f32_16x16x32_bf16 v[116:119], v[170:173], v[186:189], v[116:119]
	v_mfma_f32_16x16x32_bf16 v[112:115], v[178:181], v[186:189], v[112:115]
	v_mfma_f32_16x16x32_bf16 v[100:103], v[170:173], v[194:197], v[100:103]
	v_mfma_f32_16x16x32_bf16 v[96:99], v[178:181], v[194:197], v[96:99]
	v_mfma_f32_16x16x32_bf16 v[84:87], v[170:173], v[202:205], v[84:87]
	v_mfma_f32_16x16x32_bf16 v[80:83], v[178:181], v[202:205], v[80:83]
	v_mfma_f32_16x16x32_bf16 v[68:71], v[170:173], v[210:213], v[68:71]
	v_mfma_f32_16x16x32_bf16 v[64:67], v[178:181], v[210:213], v[64:67]
	s_barrier
	s_setprio 0
	s_add_i32 s54, s86, s48
	v_lshl_add_u64 v[214:215], s[34:35], 0, v[132:133]
	s_mov_b32 m0, s54
	ds_read_b128 v[182:185], v153 offset:16384
	ds_read_b128 v[186:189], v153 offset:17408
	ds_read_b128 v[190:193], v153 offset:18432
	ds_read_b128 v[194:197], v153 offset:19456
	ds_read_b128 v[198:201], v153 offset:20480
	ds_read_b128 v[202:205], v153 offset:21504
	ds_read_b128 v[206:209], v153 offset:22528
	ds_read_b128 v[210:213], v153 offset:23552
	global_load_lds_dwordx4 v[214:215], off
	s_add_i32 m0, s54, 0x2000
	s_add_u32 s64, s34, 0x80000
	v_lshl_add_u64 v[216:217], s[34:35], 0, v[128:129]
	s_addc_u32 s65, s35, 0
	s_add_i32 s54, s87, s48
	global_load_lds_dwordx4 v[216:217], off
	v_lshl_add_u64 v[218:219], s[64:65], 0, v[132:133]
	s_mov_b32 m0, s54
	v_lshl_add_u64 v[220:221], s[36:37], 0, v[130:131]
	global_load_lds_dwordx4 v[218:219], off
	v_lshl_add_u64 v[218:219], s[64:65], 0, v[128:129]
	s_add_i32 m0, s54, 0x2000
	s_nop 0
	global_load_lds_dwordx4 v[218:219], off
	v_lshl_add_u64 v[218:219], s[36:37], 0, v[134:135]
	s_mov_b32 m0, s75
	s_nop 0
	global_load_lds_dwordx4 v[218:219], off
	s_mov_b32 m0, s76
	s_nop 0
	global_load_lds_dwordx4 v[220:221], off
	s_waitcnt vmcnt(8)
	s_waitcnt lgkmcnt(0)
	s_setprio 1
	s_barrier
; #define PG8_STAGE(bufoff, gbase, voff) do { _Pragma("unroll") for (int _i = 0; _i < 2; ++_i) \
;         __builtin_amdgcn_global_load_lds((const unsigned*)((const char*)(gbase) + (voff)[_i]), (LAS unsigned*)(lds + (bufoff) + ldsw + _i * 8192), 16, 0, 0); } while (0)
; #define PG8_LDA(dst, b, h) do { _Pragma("unroll") for (int m = 0; m < 4; ++m) _Pragma("unroll") for (int k = 0; k < 2; ++k) dst[m][k] = *(const LAS bf16x8*)(lds + PG8_SA(b, h) + aoff + m * 2048 + k * KOFF); } while (0)
; #define PG8_LDB(dst, b, h) do { _Pragma("unroll") for (int n = 0; n < 2; ++n) _Pragma("unroll") for (int k = 0; k < 2; ++k) dst[n][k] = *(const LAS bf16x8*)(lds + PG8_SB(b, h) + boff + n * 2048 + k * KOFF); } while (0)
; #define PG8_WAIT_V(n) asm volatile("s_waitcnt vmcnt(" #n ")" ::: "memory")
; #define PG8_WAIT_L(n) asm volatile("s_waitcnt lgkmcnt(" #n ")" ::: "memory")
; #define PG8_BAR __builtin_amdgcn_s_barrier()
; #define PG8_SCHED __builtin_amdgcn_sched_barrier(0)
; template <class Epi, bool ALIGN_EPI = true, bool FP8 = false>
; __device__ __forceinline__ void gemm_phase(LAS unsigned char* lds, const Gemm g, const StaticOrder& S, const Epi& E, const int wid) {
;     ...
;             PG8_WAIT_V(8); PG8_WAIT_L(0); PG8_BAR; PG8_MMA(1, 0, At, B0); PG8_MMA(1, 1, At, B1); PG8_BAR; PG8_SCHED;
;             PG8_LDB(B0, 1, 0); PG8_LDB(B1, 1, 1); PG8_SCHED; PG8_LDA(At, 1, 0); PG8_STAGE(PG8_SA(0, 1), a2 + hstep, voffA);
;             PG8_WAIT_V(8); PG8_WAIT_L(0); PG8_BAR; PG8_MMA(0, 0, At, B0); PG8_MMA(0, 1, At, B1); PG8_BAR; PG8_SCHED;
	v_mfma_f32_16x16x32_bf16 v[60:63], v[146:149], v[182:185], v[60:63]
	v_mfma_f32_16x16x32_bf16 v[56:59], v[158:161], v[182:185], v[56:59]
	v_mfma_f32_16x16x32_bf16 v[44:47], v[146:149], v[190:193], v[44:47]
	v_mfma_f32_16x16x32_bf16 v[40:43], v[158:161], v[190:193], v[40:43]
	v_mfma_f32_16x16x32_bf16 v[28:31], v[146:149], v[198:201], v[28:31]
	v_mfma_f32_16x16x32_bf16 v[24:27], v[158:161], v[198:201], v[24:27]
	v_mfma_f32_16x16x32_bf16 v[12:15], v[146:149], v[206:209], v[12:15]
	v_mfma_f32_16x16x32_bf16 v[8:11], v[158:161], v[206:209], v[8:11]
	v_mfma_f32_16x16x32_bf16 v[60:63], v[154:157], v[186:189], v[60:63]
	v_mfma_f32_16x16x32_bf16 v[56:59], v[162:165], v[186:189], v[56:59]
	v_mfma_f32_16x16x32_bf16 v[44:47], v[154:157], v[194:197], v[44:47]
	v_mfma_f32_16x16x32_bf16 v[40:43], v[162:165], v[194:197], v[40:43]
	v_mfma_f32_16x16x32_bf16 v[28:31], v[154:157], v[202:205], v[28:31]
	v_mfma_f32_16x16x32_bf16 v[24:27], v[162:165], v[202:205], v[24:27]
	v_mfma_f32_16x16x32_bf16 v[12:15], v[154:157], v[210:213], v[12:15]
	v_mfma_f32_16x16x32_bf16 v[8:11], v[162:165], v[210:213], v[8:11]
	v_mfma_f32_16x16x32_bf16 v[52:55], v[166:169], v[182:185], v[52:55]
	v_mfma_f32_16x16x32_bf16 v[48:51], v[174:177], v[182:185], v[48:51]
	v_mfma_f32_16x16x32_bf16 v[36:39], v[166:169], v[190:193], v[36:39]
	v_mfma_f32_16x16x32_bf16 v[32:35], v[174:177], v[190:193], v[32:35]
	v_mfma_f32_16x16x32_bf16 v[20:23], v[166:169], v[198:201], v[20:23]
	v_mfma_f32_16x16x32_bf16 v[16:19], v[174:177], v[198:201], v[16:19]
	v_mfma_f32_16x16x32_bf16 v[4:7], v[166:169], v[206:209], v[4:7]
	v_mfma_f32_16x16x32_bf16 v[0:3], v[174:177], v[206:209], v[0:3]
	v_mfma_f32_16x16x32_bf16 v[52:55], v[170:173], v[186:189], v[52:55]
	v_mfma_f32_16x16x32_bf16 v[48:51], v[178:181], v[186:189], v[48:51]
	v_mfma_f32_16x16x32_bf16 v[36:39], v[170:173], v[194:197], v[36:39]
	v_mfma_f32_16x16x32_bf16 v[32:35], v[178:181], v[194:197], v[32:35]
	v_mfma_f32_16x16x32_bf16 v[20:23], v[170:173], v[202:205], v[20:23]
	v_mfma_f32_16x16x32_bf16 v[16:19], v[178:181], v[202:205], v[16:19]
	v_mfma_f32_16x16x32_bf16 v[4:7], v[170:173], v[210:213], v[4:7]
	v_mfma_f32_16x16x32_bf16 v[0:3], v[178:181], v[210:213], v[0:3]
	s_barrier
	s_setprio 0
	s_add_i32 s54, 0, 0x18000
	s_add_i32 s64, 0, 0x1c000
	v_add_u32_e32 v162, s54, v150
	v_add_u32_e32 v178, s64, v150
	ds_read_b128 v[146:149], v162
	ds_read_b128 v[154:157], v162 offset:1024
	ds_read_b128 v[158:161], v162 offset:2048
	ds_read_b128 v[162:165], v162 offset:3072
	ds_read_b128 v[166:169], v178
	ds_read_b128 v[170:173], v178 offset:1024
	ds_read_b128 v[174:177], v178 offset:2048
	ds_read_b128 v[178:181], v178 offset:3072
	s_add_u32 s36, s36, 0x80000
	s_addc_u32 s37, s37, 0
	s_mov_b32 m0, s77
	v_lshl_add_u64 v[222:223], s[36:37], 0, v[134:135]
	ds_read_b128 v[182:185], v153 offset:32768
	ds_read_b128 v[186:189], v153 offset:33792
	ds_read_b128 v[190:193], v153 offset:34816
	ds_read_b128 v[194:197], v153 offset:35840
	ds_read_b128 v[198:201], v153 offset:36864
	ds_read_b128 v[202:205], v153 offset:37888
	ds_read_b128 v[206:209], v153 offset:38912
	ds_read_b128 v[210:213], v153 offset:39936
	global_load_lds_dwordx4 v[222:223], off
	v_lshl_add_u64 v[222:223], s[36:37], 0, v[130:131]
	s_mov_b32 m0, s78
	s_nop 0
	global_load_lds_dwordx4 v[222:223], off
	s_waitcnt vmcnt(8)
	s_waitcnt lgkmcnt(0)
	s_setprio 1
	s_barrier
	v_mfma_f32_16x16x32_bf16 v[124:127], v[146:149], v[182:185], v[124:127]
	v_mfma_f32_16x16x32_bf16 v[120:123], v[158:161], v[182:185], v[120:123]
	v_mfma_f32_16x16x32_bf16 v[108:111], v[146:149], v[190:193], v[108:111]
	v_mfma_f32_16x16x32_bf16 v[104:107], v[158:161], v[190:193], v[104:107]
	v_mfma_f32_16x16x32_bf16 v[92:95], v[146:149], v[198:201], v[92:95]
	v_mfma_f32_16x16x32_bf16 v[88:91], v[158:161], v[198:201], v[88:91]
	v_mfma_f32_16x16x32_bf16 v[76:79], v[146:149], v[206:209], v[76:79]
	v_mfma_f32_16x16x32_bf16 v[72:75], v[158:161], v[206:209], v[72:75]
	v_mfma_f32_16x16x32_bf16 v[124:127], v[154:157], v[186:189], v[124:127]
	v_mfma_f32_16x16x32_bf16 v[120:123], v[162:165], v[186:189], v[120:123]
	v_mfma_f32_16x16x32_bf16 v[108:111], v[154:157], v[194:197], v[108:111]
	v_mfma_f32_16x16x32_bf16 v[104:107], v[162:165], v[194:197], v[104:107]
	v_mfma_f32_16x16x32_bf16 v[92:95], v[154:157], v[202:205], v[92:95]
	v_mfma_f32_16x16x32_bf16 v[88:91], v[162:165], v[202:205], v[88:91]
	v_mfma_f32_16x16x32_bf16 v[76:79], v[154:157], v[210:213], v[76:79]
	v_mfma_f32_16x16x32_bf16 v[72:75], v[162:165], v[210:213], v[72:75]
	v_mfma_f32_16x16x32_bf16 v[116:119], v[166:169], v[182:185], v[116:119]
	v_mfma_f32_16x16x32_bf16 v[112:115], v[174:177], v[182:185], v[112:115]
	v_mfma_f32_16x16x32_bf16 v[100:103], v[166:169], v[190:193], v[100:103]
	v_mfma_f32_16x16x32_bf16 v[96:99], v[174:177], v[190:193], v[96:99]
	v_mfma_f32_16x16x32_bf16 v[84:87], v[166:169], v[198:201], v[84:87]
	v_mfma_f32_16x16x32_bf16 v[80:83], v[174:177], v[198:201], v[80:83]
	v_mfma_f32_16x16x32_bf16 v[68:71], v[166:169], v[206:209], v[68:71]
	v_mfma_f32_16x16x32_bf16 v[64:67], v[174:177], v[206:209], v[64:67]
	v_mfma_f32_16x16x32_bf16 v[116:119], v[170:173], v[186:189], v[116:119]
	v_mfma_f32_16x16x32_bf16 v[112:115], v[178:181], v[186:189], v[112:115]
	v_mfma_f32_16x16x32_bf16 v[100:103], v[170:173], v[194:197], v[100:103]
	v_mfma_f32_16x16x32_bf16 v[96:99], v[178:181], v[194:197], v[96:99]
	v_mfma_f32_16x16x32_bf16 v[84:87], v[170:173], v[202:205], v[84:87]
	v_mfma_f32_16x16x32_bf16 v[80:83], v[178:181], v[202:205], v[80:83]
	v_mfma_f32_16x16x32_bf16 v[68:71], v[170:173], v[210:213], v[68:71]
	v_mfma_f32_16x16x32_bf16 v[64:67], v[178:181], v[210:213], v[64:67]
	s_barrier
; #define PG8_STAGE(bufoff, gbase, voff) do { _Pragma("unroll") for (int _i = 0; _i < 2; ++_i) \
;         __builtin_amdgcn_global_load_lds((const unsigned*)((const char*)(gbase) + (voff)[_i]), (LAS unsigned*)(lds + (bufoff) + ldsw + _i * 8192), 16, 0, 0); } while (0)
; #define PG8_LDA(dst, b, h) do { _Pragma("unroll") for (int m = 0; m < 4; ++m) _Pragma("unroll") for (int k = 0; k < 2; ++k) dst[m][k] = *(const LAS bf16x8*)(lds + PG8_SA(b, h) + aoff + m * 2048 + k * KOFF); } while (0)
; #define PG8_WAIT_V(n) asm volatile("s_waitcnt vmcnt(" #n ")" ::: "memory")
; #define PG8_WAIT_L(n) asm volatile("s_waitcnt lgkmcnt(" #n ")" ::: "memory")
; #define PG8_BAR __builtin_amdgcn_s_barrier()
; #define PG8_SCHED __builtin_amdgcn_sched_barrier(0)
; template <class Epi, bool ALIGN_EPI = true, bool FP8 = false>
; __device__ __forceinline__ void gemm_phase(LAS unsigned char* lds, const Gemm g, const StaticOrder& S, const Epi& E, const int wid) {
;     ...
;             PG8_LDA(At, 1, 1); PG8_STAGE(PG8_SB(1, 0), b3, voffB); PG8_STAGE(PG8_SB(1, 1), b3 + hstep, voffB); PG8_STAGE(PG8_SA(1, 0), a3, voffA);
;             PG8_WAIT_V(8); PG8_WAIT_L(0); PG8_BAR; PG8_MMA(1, 0, At, B0); PG8_MMA(1, 1, At, B1); PG8_BAR; PG8_SCHED;
;         }
	s_setprio 0
	s_add_i32 s36, s54, s48
	v_lshl_add_u64 v[214:215], v[214:215], 0, s[16:17]
	s_mov_b32 m0, s36
	ds_read_b128 v[182:185], v153 offset:49152
	ds_read_b128 v[186:189], v153 offset:50176
	ds_read_b128 v[190:193], v153 offset:51200
	ds_read_b128 v[194:197], v153 offset:52224
	ds_read_b128 v[198:201], v153 offset:53248
	ds_read_b128 v[202:205], v153 offset:54272
	ds_read_b128 v[206:209], v153 offset:55296
	ds_read_b128 v[210:213], v153 offset:56320
	global_load_lds_dwordx4 v[214:215], off
	s_add_i32 m0, s36, 0x2000
	s_add_u32 s34, s34, 0x80080
	v_lshl_add_u64 v[214:215], v[216:217], 0, s[16:17]
	s_addc_u32 s35, s35, 0
	s_add_i32 s36, s64, s48
	global_load_lds_dwordx4 v[214:215], off
	v_lshl_add_u64 v[214:215], s[34:35], 0, v[132:133]
	s_mov_b32 m0, s36
	s_nop 0
	global_load_lds_dwordx4 v[214:215], off
	v_lshl_add_u64 v[214:215], s[34:35], 0, v[128:129]
	s_add_i32 m0, s36, 0x2000
	s_nop 0
	global_load_lds_dwordx4 v[214:215], off
	v_lshl_add_u64 v[214:215], v[218:219], 0, s[16:17]
	s_mov_b32 m0, s83
	s_nop 0
	global_load_lds_dwordx4 v[214:215], off
	v_lshl_add_u64 v[214:215], v[220:221], 0, s[16:17]
	s_mov_b32 m0, s84
	s_nop 0
	global_load_lds_dwordx4 v[214:215], off
	s_waitcnt vmcnt(8)
	s_waitcnt lgkmcnt(0)
	s_setprio 1
	s_barrier
	v_mfma_f32_16x16x32_bf16 v[60:63], v[146:149], v[182:185], v[60:63]
	v_mfma_f32_16x16x32_bf16 v[56:59], v[158:161], v[182:185], v[56:59]
	v_mfma_f32_16x16x32_bf16 v[44:47], v[146:149], v[190:193], v[44:47]
	v_mfma_f32_16x16x32_bf16 v[40:43], v[158:161], v[190:193], v[40:43]
	v_mfma_f32_16x16x32_bf16 v[28:31], v[146:149], v[198:201], v[28:31]
	v_mfma_f32_16x16x32_bf16 v[24:27], v[158:161], v[198:201], v[24:27]
	v_mfma_f32_16x16x32_bf16 v[12:15], v[146:149], v[206:209], v[12:15]
	v_mfma_f32_16x16x32_bf16 v[8:11], v[158:161], v[206:209], v[8:11]
	v_mfma_f32_16x16x32_bf16 v[60:63], v[154:157], v[186:189], v[60:63]
	v_mfma_f32_16x16x32_bf16 v[56:59], v[162:165], v[186:189], v[56:59]
	v_mfma_f32_16x16x32_bf16 v[44:47], v[154:157], v[194:197], v[44:47]
	v_mfma_f32_16x16x32_bf16 v[40:43], v[162:165], v[194:197], v[40:43]
	v_mfma_f32_16x16x32_bf16 v[28:31], v[154:157], v[202:205], v[28:31]
	v_mfma_f32_16x16x32_bf16 v[24:27], v[162:165], v[202:205], v[24:27]
	v_mfma_f32_16x16x32_bf16 v[12:15], v[154:157], v[210:213], v[12:15]
	v_mfma_f32_16x16x32_bf16 v[8:11], v[162:165], v[210:213], v[8:11]
	v_mfma_f32_16x16x32_bf16 v[52:55], v[166:169], v[182:185], v[52:55]
	v_mfma_f32_16x16x32_bf16 v[48:51], v[174:177], v[182:185], v[48:51]
	v_mfma_f32_16x16x32_bf16 v[36:39], v[166:169], v[190:193], v[36:39]
	v_mfma_f32_16x16x32_bf16 v[32:35], v[174:177], v[190:193], v[32:35]
	v_mfma_f32_16x16x32_bf16 v[20:23], v[166:169], v[198:201], v[20:23]
	v_mfma_f32_16x16x32_bf16 v[16:19], v[174:177], v[198:201], v[16:19]
	v_mfma_f32_16x16x32_bf16 v[4:7], v[166:169], v[206:209], v[4:7]
	v_mfma_f32_16x16x32_bf16 v[0:3], v[174:177], v[206:209], v[0:3]
	v_mfma_f32_16x16x32_bf16 v[52:55], v[170:173], v[186:189], v[52:55]
	v_mfma_f32_16x16x32_bf16 v[48:51], v[178:181], v[186:189], v[48:51]
	v_mfma_f32_16x16x32_bf16 v[36:39], v[170:173], v[194:197], v[36:39]
	v_mfma_f32_16x16x32_bf16 v[32:35], v[178:181], v[194:197], v[32:35]
	v_mfma_f32_16x16x32_bf16 v[20:23], v[170:173], v[202:205], v[20:23]
	v_mfma_f32_16x16x32_bf16 v[16:19], v[178:181], v[202:205], v[16:19]
	v_mfma_f32_16x16x32_bf16 v[4:7], v[170:173], v[210:213], v[4:7]
	v_mfma_f32_16x16x32_bf16 v[0:3], v[178:181], v[210:213], v[0:3]
	s_barrier
	s_setprio 0
	s_add_u32 s30, s30, 0x100
	s_addc_u32 s31, s31, 0
	s_add_u32 s42, s42, 0x100
	s_addc_u32 s43, s43, 0
	s_cmp_ge_u32 s52, s9
	s_mov_b32 s34, s52
	s_cbranch_scc0 .LBB0_506
	s_and_b64 vcc, exec, s[12:13]
	s_cbranch_vccz .LBB0_509

; #define PG8_STAGE(bufoff, gbase, voff) do { _Pragma("unroll") for (int _i = 0; _i < 2; ++_i) \
;         __builtin_amdgcn_global_load_lds((const unsigned*)((const char*)(gbase) + (voff)[_i]), (LAS unsigned*)(lds + (bufoff) + ldsw + _i * 8192), 16, 0, 0); } while (0)
; #define PG8_LDA(dst, b, h) do { _Pragma("unroll") for (int m = 0; m < 4; ++m) _Pragma("unroll") for (int k = 0; k < 2; ++k) dst[m][k] = *(const LAS bf16x8*)(lds + PG8_SA(b, h) + aoff + m * 2048 + k * KOFF); } while (0)
; #define PG8_LDB(dst, b, h) do { _Pragma("unroll") for (int n = 0; n < 2; ++n) _Pragma("unroll") for (int k = 0; k < 2; ++k) dst[n][k] = *(const LAS bf16x8*)(lds + PG8_SB(b, h) + boff + n * 2048 + k * KOFF); } while (0)
; #define PG8_WAIT_V(n) asm volatile("s_waitcnt vmcnt(" #n ")" ::: "memory")
; #define PG8_WAIT_L(n) asm volatile("s_waitcnt lgkmcnt(" #n ")" ::: "memory")
; #define PG8_BAR __builtin_amdgcn_s_barrier()
; #define PG8_SCHED __builtin_amdgcn_sched_barrier(0)
; template <class Epi, bool ALIGN_EPI = true, bool FP8 = false>
; __device__ __forceinline__ void gemm_phase(LAS unsigned char* lds, const Gemm g, const StaticOrder& S, const Epi& E, const int wid) {
;     ...
;             PG8_LDB(B0, 0, 0); PG8_LDB(B1, 0, 1); PG8_SCHED; PG8_LDA(At, 0, 0); PG8_STAGE(PG8_SA(1, 1), a1 + hstep, voffA);
;             PG8_WAIT_V(8); PG8_WAIT_L(0); PG8_BAR; PG8_MMA(0, 0, At, B0); PG8_MMA(0, 1, At, B1); PG8_BAR; PG8_SCHED;
;             PG8_LDA(At, 0, 1); PG8_STAGE(PG8_SB(0, 0), b2, voffB); PG8_STAGE(PG8_SB(0, 1), b2 + hstep, voffB); PG8_STAGE(PG8_SA(0, 0), a2, voffA);
;             PG8_WAIT_V(8); PG8_WAIT_L(0); PG8_BAR; PG8_MMA(1, 0, At, B0); PG8_MMA(1, 1, At, B1); PG8_BAR; PG8_SCHED;
;             PG8_LDB(B0, 1, 0); PG8_LDB(B1, 1, 1); PG8_SCHED; PG8_LDA(At, 1, 0); PG8_STAGE(PG8_SA(0, 1), a2 + hstep, voffA);
.LBB0_572:
	ds_read_b128 v[152:155], v190
	ds_read_b128 v[156:159], v190 offset:1024
	ds_read_b128 v[144:147], v190 offset:2048
	ds_read_b128 v[148:151], v190 offset:3072
	ds_read_b128 v[136:139], v191
	ds_read_b128 v[140:143], v191 offset:1024
	ds_read_b128 v[128:131], v191 offset:2048
	ds_read_b128 v[132:135], v191 offset:3072
	s_add_i32 s3, s34, 2
	s_add_u32 s35, s30, 0xfffc0080
	s_addc_u32 s36, s31, -1
	s_cmp_eq_u32 s86, s34
	s_cselect_b32 s34, s85, s87
	s_cselect_b32 s37, s21, s36
	s_cselect_b32 s36, s23, s35
	s_cselect_b32 s35, s84, s88
	v_lshl_add_u64 v[220:221], s[30:31], 0, v[170:171]
	s_add_i32 m0, s27, 0xc000
	ds_read_b128 v[178:181], v192
	ds_read_b128 v[182:185], v192 offset:1024
	ds_read_b128 v[196:199], v192 offset:2048
	ds_read_b128 v[200:203], v192 offset:3072
	ds_read_b128 v[204:207], v192 offset:4096
	ds_read_b128 v[208:211], v192 offset:5120
	ds_read_b128 v[212:215], v192 offset:6144
	ds_read_b128 v[216:219], v192 offset:7168
	global_load_lds_dwordx4 v[220:221], off
	v_lshl_add_u64 v[220:221], s[30:31], 0, v[172:173]
	s_add_i32 m0, s27, 0xe000
	s_nop 0
	global_load_lds_dwordx4 v[220:221], off
	s_waitcnt vmcnt(8)
	s_waitcnt lgkmcnt(0)
	s_setprio 1
	s_barrier
	v_mfma_f32_16x16x128_f8f6f4 v[120:123], v[152:159], v[178:185], v[120:123]
	v_mfma_f32_16x16x128_f8f6f4 v[124:127], v[144:151], v[178:185], v[124:127]
	v_mfma_f32_16x16x128_f8f6f4 v[112:115], v[152:159], v[196:203], v[112:115]
	v_mfma_f32_16x16x128_f8f6f4 v[116:119], v[144:151], v[196:203], v[116:119]
	v_mfma_f32_16x16x128_f8f6f4 v[104:107], v[152:159], v[204:211], v[104:107]
	v_mfma_f32_16x16x128_f8f6f4 v[108:111], v[144:151], v[204:211], v[108:111]
	v_mfma_f32_16x16x128_f8f6f4 v[88:91], v[152:159], v[212:219], v[88:91]
	v_mfma_f32_16x16x128_f8f6f4 v[92:95], v[144:151], v[212:219], v[92:95]
	v_mfma_f32_16x16x128_f8f6f4 v[96:99], v[136:143], v[178:185], v[96:99]
	v_mfma_f32_16x16x128_f8f6f4 v[100:103], v[128:135], v[178:185], v[100:103]
	v_mfma_f32_16x16x128_f8f6f4 v[80:83], v[136:143], v[196:203], v[80:83]
	v_mfma_f32_16x16x128_f8f6f4 v[84:87], v[128:135], v[196:203], v[84:87]
	v_mfma_f32_16x16x128_f8f6f4 v[72:75], v[136:143], v[204:211], v[72:75]
	v_mfma_f32_16x16x128_f8f6f4 v[76:79], v[128:135], v[204:211], v[76:79]
	v_mfma_f32_16x16x128_f8f6f4 v[64:67], v[136:143], v[212:219], v[64:67]
	v_mfma_f32_16x16x128_f8f6f4 v[68:71], v[128:135], v[212:219], v[68:71]
	s_barrier
	s_setprio 0
	s_add_i32 s42, s75, s48
	v_lshl_add_u64 v[178:179], s[34:35], 0, v[164:165]
	s_mov_b32 m0, s42
	ds_read_b128 v[196:199], v192 offset:16384
	ds_read_b128 v[200:203], v192 offset:17408
	ds_read_b128 v[204:207], v192 offset:18432
	ds_read_b128 v[208:211], v192 offset:19456
	ds_read_b128 v[212:215], v192 offset:20480
	ds_read_b128 v[216:219], v192 offset:21504
	ds_read_b128 v[220:223], v192 offset:22528
	ds_read_b128 v[224:227], v192 offset:23552
	global_load_lds_dwordx4 v[178:179], off
	s_add_i32 m0, s42, 0x2000
	s_add_u32 s42, s34, 0x40000
	v_lshl_add_u64 v[180:181], s[34:35], 0, v[160:161]
	s_addc_u32 s43, s35, 0
	s_add_i32 s52, s76, s48
	global_load_lds_dwordx4 v[180:181], off
	v_lshl_add_u64 v[182:183], s[42:43], 0, v[164:165]
	s_mov_b32 m0, s52
	v_lshl_add_u64 v[184:185], s[36:37], 0, v[162:163]
	global_load_lds_dwordx4 v[182:183], off
	v_lshl_add_u64 v[182:183], s[42:43], 0, v[160:161]
	s_add_i32 m0, s52, 0x2000
	s_nop 0
	global_load_lds_dwordx4 v[182:183], off
	v_lshl_add_u64 v[182:183], s[36:37], 0, v[166:167]
	s_mov_b32 m0, s27
	s_nop 0
	global_load_lds_dwordx4 v[182:183], off
	s_mov_b32 m0, s55
	s_nop 0
	global_load_lds_dwordx4 v[184:185], off
	s_waitcnt vmcnt(8)
	s_waitcnt lgkmcnt(0)
	s_setprio 1
	s_barrier
	v_mfma_f32_16x16x128_f8f6f4 v[56:59], v[152:159], v[196:203], v[56:59]
	v_mfma_f32_16x16x128_f8f6f4 v[60:63], v[144:151], v[196:203], v[60:63]
	v_mfma_f32_16x16x128_f8f6f4 v[48:51], v[152:159], v[204:211], v[48:51]
	v_mfma_f32_16x16x128_f8f6f4 v[52:55], v[144:151], v[204:211], v[52:55]
	v_mfma_f32_16x16x128_f8f6f4 v[40:43], v[152:159], v[212:219], v[40:43]
	v_mfma_f32_16x16x128_f8f6f4 v[44:47], v[144:151], v[212:219], v[44:47]
	v_mfma_f32_16x16x128_f8f6f4 v[228:231], v[152:159], v[220:227], v[24:27]
	v_mfma_f32_16x16x128_f8f6f4 v[232:235], v[144:151], v[220:227], v[28:31]
	v_mfma_f32_16x16x128_f8f6f4 v[236:239], v[136:143], v[196:203], v[32:35]
	v_mfma_f32_16x16x128_f8f6f4 v[240:243], v[128:135], v[196:203], v[36:39]
	v_mfma_f32_16x16x128_f8f6f4 v[244:247], v[136:143], v[204:211], v[16:19]
	v_mfma_f32_16x16x128_f8f6f4 v[204:207], v[128:135], v[204:211], v[20:23]
	v_mfma_f32_16x16x128_f8f6f4 v[208:211], v[136:143], v[212:219], v[8:11]
	v_mfma_f32_16x16x128_f8f6f4 v[212:215], v[128:135], v[212:219], v[12:15]
	v_mfma_f32_16x16x128_f8f6f4 v[216:219], v[136:143], v[220:227], v[0:3]
	v_mfma_f32_16x16x128_f8f6f4 v[220:223], v[128:135], v[220:227], v[4:7]
	s_barrier
	s_setprio 0
	s_add_i32 s42, 0, 0x18000
	s_add_i32 s43, 0, 0x1c000
	s_nop 0
	v_add_u32_e32 v12, s42, v187
	v_add_u32_e32 v16, s43, v187
	ds_read_b128 v[0:3], v12
	ds_read_b128 v[4:7], v12 offset:1024
	ds_read_b128 v[8:11], v12 offset:2048
	ds_read_b128 v[12:15], v12 offset:3072
	ds_read_b128 v[128:131], v16
	ds_read_b128 v[132:135], v16 offset:1024
	ds_read_b128 v[136:139], v16 offset:2048
	ds_read_b128 v[140:143], v16 offset:3072
	s_add_u32 s36, s36, 0x40000
	s_addc_u32 s37, s37, 0
	s_mov_b32 m0, s64
	v_lshl_add_u64 v[152:153], s[36:37], 0, v[166:167]
	ds_read_b128 v[16:19], v192 offset:32768
	ds_read_b128 v[20:23], v192 offset:33792
	ds_read_b128 v[24:27], v192 offset:34816
	ds_read_b128 v[28:31], v192 offset:35840
	ds_read_b128 v[32:35], v192 offset:36864
	ds_read_b128 v[36:39], v192 offset:37888
	ds_read_b128 v[144:147], v192 offset:38912
	ds_read_b128 v[148:151], v192 offset:39936
	global_load_lds_dwordx4 v[152:153], off
	v_lshl_add_u64 v[152:153], s[36:37], 0, v[162:163]
	s_mov_b32 m0, s65
	s_nop 0
	global_load_lds_dwordx4 v[152:153], off
	s_waitcnt vmcnt(8)
	s_waitcnt lgkmcnt(0)
	s_setprio 1
	s_barrier
; #define PG8_STAGE(bufoff, gbase, voff) do { _Pragma("unroll") for (int _i = 0; _i < 2; ++_i) \
;         __builtin_amdgcn_global_load_lds((const unsigned*)((const char*)(gbase) + (voff)[_i]), (LAS unsigned*)(lds + (bufoff) + ldsw + _i * 8192), 16, 0, 0); } while (0)
; #define PG8_LDA(dst, b, h) do { _Pragma("unroll") for (int m = 0; m < 4; ++m) _Pragma("unroll") for (int k = 0; k < 2; ++k) dst[m][k] = *(const LAS bf16x8*)(lds + PG8_SA(b, h) + aoff + m * 2048 + k * KOFF); } while (0)
; #define PG8_WAIT_V(n) asm volatile("s_waitcnt vmcnt(" #n ")" ::: "memory")
; #define PG8_WAIT_L(n) asm volatile("s_waitcnt lgkmcnt(" #n ")" ::: "memory")
; #define PG8_BAR __builtin_amdgcn_s_barrier()
; #define PG8_SCHED __builtin_amdgcn_sched_barrier(0)
; template <class Epi, bool ALIGN_EPI = true, bool FP8 = false>
; __device__ __forceinline__ void gemm_phase(LAS unsigned char* lds, const Gemm g, const StaticOrder& S, const Epi& E, const int wid) {
;     ...
;             PG8_WAIT_V(8); PG8_WAIT_L(0); PG8_BAR; PG8_MMA(0, 0, At, B0); PG8_MMA(0, 1, At, B1); PG8_BAR; PG8_SCHED;
;             PG8_LDA(At, 1, 1); PG8_STAGE(PG8_SB(1, 0), b3, voffB); PG8_STAGE(PG8_SB(1, 1), b3 + hstep, voffB); PG8_STAGE(PG8_SA(1, 0), a3, voffA);
;             PG8_WAIT_V(8); PG8_WAIT_L(0); PG8_BAR; PG8_MMA(1, 0, At, B0); PG8_MMA(1, 1, At, B1); PG8_BAR; PG8_SCHED;
;         }
	v_mfma_f32_16x16x128_f8f6f4 v[120:123], v[0:7], v[16:23], v[120:123]
	v_mfma_f32_16x16x128_f8f6f4 v[124:127], v[8:15], v[16:23], v[124:127]
	v_mfma_f32_16x16x128_f8f6f4 v[112:115], v[0:7], v[24:31], v[112:115]
	v_mfma_f32_16x16x128_f8f6f4 v[116:119], v[8:15], v[24:31], v[116:119]
	v_mfma_f32_16x16x128_f8f6f4 v[104:107], v[0:7], v[32:39], v[104:107]
	v_mfma_f32_16x16x128_f8f6f4 v[108:111], v[8:15], v[32:39], v[108:111]
	v_mfma_f32_16x16x128_f8f6f4 v[88:91], v[0:7], v[144:151], v[88:91]
	v_mfma_f32_16x16x128_f8f6f4 v[92:95], v[8:15], v[144:151], v[92:95]
	v_mfma_f32_16x16x128_f8f6f4 v[96:99], v[128:135], v[16:23], v[96:99]
	v_mfma_f32_16x16x128_f8f6f4 v[100:103], v[136:143], v[16:23], v[100:103]
	v_mfma_f32_16x16x128_f8f6f4 v[80:83], v[128:135], v[24:31], v[80:83]
	v_mfma_f32_16x16x128_f8f6f4 v[84:87], v[136:143], v[24:31], v[84:87]
	v_mfma_f32_16x16x128_f8f6f4 v[72:75], v[128:135], v[32:39], v[72:75]
	v_mfma_f32_16x16x128_f8f6f4 v[76:79], v[136:143], v[32:39], v[76:79]
	v_mfma_f32_16x16x128_f8f6f4 v[64:67], v[128:135], v[144:151], v[64:67]
	v_mfma_f32_16x16x128_f8f6f4 v[68:71], v[136:143], v[144:151], v[68:71]
	s_barrier
	s_setprio 0
	s_add_i32 s36, s42, s48
	v_lshl_add_u64 v[24:25], v[178:179], 0, s[8:9]
	s_mov_b32 m0, s36
	ds_read_b128 v[16:19], v192 offset:49152
	ds_read_b128 v[20:23], v192 offset:50176
	ds_read_b128 v[144:147], v192 offset:51200
	ds_read_b128 v[148:151], v192 offset:52224
	ds_read_b128 v[152:155], v192 offset:53248
	ds_read_b128 v[156:159], v192 offset:54272
	ds_read_b128 v[196:199], v192 offset:55296
	ds_read_b128 v[200:203], v192 offset:56320
	global_load_lds_dwordx4 v[24:25], off
	s_add_i32 m0, s36, 0x2000
	s_add_u32 s34, s34, 0x40080
	v_lshl_add_u64 v[24:25], v[180:181], 0, s[8:9]
	s_addc_u32 s35, s35, 0
	s_add_i32 s36, s43, s48
	global_load_lds_dwordx4 v[24:25], off
	v_lshl_add_u64 v[24:25], s[34:35], 0, v[164:165]
	s_mov_b32 m0, s36
	s_nop 0
	global_load_lds_dwordx4 v[24:25], off
	v_lshl_add_u64 v[24:25], s[34:35], 0, v[160:161]
	s_add_i32 m0, s36, 0x2000
	s_nop 0
	global_load_lds_dwordx4 v[24:25], off
	v_lshl_add_u64 v[24:25], v[182:183], 0, s[8:9]
	s_mov_b32 m0, s70
	s_nop 0
	global_load_lds_dwordx4 v[24:25], off
	v_lshl_add_u64 v[24:25], v[184:185], 0, s[8:9]
	s_mov_b32 m0, s71
	s_nop 0
	global_load_lds_dwordx4 v[24:25], off
	s_waitcnt vmcnt(8)
	s_waitcnt lgkmcnt(0)
	s_setprio 1
	s_barrier
	v_mfma_f32_16x16x128_f8f6f4 v[56:59], v[0:7], v[16:23], v[56:59]
	v_mfma_f32_16x16x128_f8f6f4 v[60:63], v[8:15], v[16:23], v[60:63]
	v_mfma_f32_16x16x128_f8f6f4 v[48:51], v[0:7], v[144:151], v[48:51]
	v_mfma_f32_16x16x128_f8f6f4 v[52:55], v[8:15], v[144:151], v[52:55]
	v_mfma_f32_16x16x128_f8f6f4 v[40:43], v[0:7], v[152:159], v[40:43]
	v_mfma_f32_16x16x128_f8f6f4 v[44:47], v[8:15], v[152:159], v[44:47]
	v_mfma_f32_16x16x128_f8f6f4 v[24:27], v[0:7], v[196:203], v[228:231]
	v_mfma_f32_16x16x128_f8f6f4 v[28:31], v[8:15], v[196:203], v[232:235]
	v_mfma_f32_16x16x128_f8f6f4 v[32:35], v[128:135], v[16:23], v[236:239]
	v_mfma_f32_16x16x128_f8f6f4 v[36:39], v[136:143], v[16:23], v[240:243]
	v_mfma_f32_16x16x128_f8f6f4 v[16:19], v[128:135], v[144:151], v[244:247]
	v_mfma_f32_16x16x128_f8f6f4 v[20:23], v[136:143], v[144:151], v[204:207]
	v_mfma_f32_16x16x128_f8f6f4 v[8:11], v[128:135], v[152:159], v[208:211]
	v_mfma_f32_16x16x128_f8f6f4 v[12:15], v[136:143], v[152:159], v[212:215]
	v_mfma_f32_16x16x128_f8f6f4 v[0:3], v[128:135], v[196:203], v[216:219]
	v_mfma_f32_16x16x128_f8f6f4 v[4:7], v[136:143], v[196:203], v[220:223]
	s_barrier
	s_setprio 0
	s_add_u32 s30, s30, 0x100
	s_addc_u32 s31, s31, 0
	s_add_u32 s87, s87, 0x100
	s_addc_u32 s88, s88, 0
	s_cmp_ge_u32 s3, s83
	s_mov_b32 s34, s3
	s_cbranch_scc0 .LBB0_572
;     __device__ __forceinline__ void operator()(const Acc& acc, const Unit& u, int wr, int wc, int fr, int fq) const {
;     ...
;                         const f32x4 v0 = acc[ai][bj][m][0] * QS, v1 = acc[ai][bj][m][1] * QS;
;     ...
;                         const f32x4 v0 = acc[ai][bj][m][0] * QS, v1 = acc[ai][bj][m][1] * QS;
	v_pk_mul_f32 v[122:123], v[122:123], s[14:15] op_sel_hi:[1,0]
	v_pk_mul_f32 v[128:129], v[120:121], s[14:15] op_sel_hi:[1,0]
	v_pk_mul_f32 v[120:121], v[126:127], s[14:15] op_sel_hi:[1,0]
	v_pk_mul_f32 v[124:125], v[124:125], s[14:15] op_sel_hi:[1,0]
	v_pk_mul_f32 v[132:133], v[98:99], s[14:15] op_sel_hi:[1,0]
	v_pk_mul_f32 v[136:137], v[96:97], s[14:15] op_sel_hi:[1,0]
	v_pk_mul_f32 v[130:131], v[102:103], s[14:15] op_sel_hi:[1,0]
	v_pk_mul_f32 v[134:135], v[100:101], s[14:15] op_sel_hi:[1,0]
	v_pk_mul_f32 v[100:101], v[114:115], s[14:15] op_sel_hi:[1,0]
	v_pk_mul_f32 v[112:113], v[112:113], s[14:15] op_sel_hi:[1,0]
	v_pk_mul_f32 v[96:97], v[118:119], s[14:15] op_sel_hi:[1,0]
	v_pk_mul_f32 v[102:103], v[116:117], s[14:15] op_sel_hi:[1,0]
	v_pk_mul_f32 v[116:117], v[82:83], s[14:15] op_sel_hi:[1,0]
	v_pk_mul_f32 v[126:127], v[80:81], s[14:15] op_sel_hi:[1,0]
	v_pk_mul_f32 v[114:115], v[86:87], s[14:15] op_sel_hi:[1,0]
	v_pk_mul_f32 v[118:119], v[84:85], s[14:15] op_sel_hi:[1,0]
	v_pk_mul_f32 v[82:83], v[106:107], s[14:15] op_sel_hi:[1,0]
	v_pk_mul_f32 v[86:87], v[104:105], s[14:15] op_sel_hi:[1,0]
	v_pk_mul_f32 v[80:81], v[110:111], s[14:15] op_sel_hi:[1,0]
	v_pk_mul_f32 v[84:85], v[108:109], s[14:15] op_sel_hi:[1,0]
	v_pk_mul_f32 v[104:105], v[74:75], s[14:15] op_sel_hi:[1,0]
	v_pk_mul_f32 v[108:109], v[72:73], s[14:15] op_sel_hi:[1,0]
	v_pk_mul_f32 v[98:99], v[78:79], s[14:15] op_sel_hi:[1,0]
	v_pk_mul_f32 v[106:107], v[76:77], s[14:15] op_sel_hi:[1,0]
	v_pk_mul_f32 v[74:75], v[90:91], s[14:15] op_sel_hi:[1,0]
	v_pk_mul_f32 v[78:79], v[88:89], s[14:15] op_sel_hi:[1,0]
	v_pk_mul_f32 v[72:73], v[94:95], s[14:15] op_sel_hi:[1,0]
	v_pk_mul_f32 v[76:77], v[92:93], s[14:15] op_sel_hi:[1,0]
	v_pk_mul_f32 v[66:67], v[66:67], s[14:15] op_sel_hi:[1,0]
	v_pk_mul_f32 v[88:89], v[64:65], s[14:15] op_sel_hi:[1,0]
	v_pk_mul_f32 v[64:65], v[70:71], s[14:15] op_sel_hi:[1,0]
	v_pk_mul_f32 v[68:69], v[68:69], s[14:15] op_sel_hi:[1,0]
	v_pk_mul_f32 v[58:59], v[58:59], s[14:15] op_sel_hi:[1,0]
	v_pk_mul_f32 v[70:71], v[56:57], s[14:15] op_sel_hi:[1,0]
	v_pk_mul_f32 v[56:57], v[62:63], s[14:15] op_sel_hi:[1,0]
	v_pk_mul_f32 v[60:61], v[60:61], s[14:15] op_sel_hi:[1,0]
	v_pk_mul_f32 v[92:93], v[34:35], s[14:15] op_sel_hi:[1,0]
	v_pk_mul_f32 v[110:111], v[32:33], s[14:15] op_sel_hi:[1,0]
	v_pk_mul_f32 v[90:91], v[38:39], s[14:15] op_sel_hi:[1,0]
	v_pk_mul_f32 v[94:95], v[36:37], s[14:15] op_sel_hi:[1,0]
	v_pk_mul_f32 v[36:37], v[50:51], s[14:15] op_sel_hi:[1,0]
	v_pk_mul_f32 v[48:49], v[48:49], s[14:15] op_sel_hi:[1,0]
	v_pk_mul_f32 v[32:33], v[54:55], s[14:15] op_sel_hi:[1,0]
	v_pk_mul_f32 v[38:39], v[52:53], s[14:15] op_sel_hi:[1,0]
	v_pk_mul_f32 v[52:53], v[18:19], s[14:15] op_sel_hi:[1,0]
	v_pk_mul_f32 v[62:63], v[16:17], s[14:15] op_sel_hi:[1,0]
	v_pk_mul_f32 v[50:51], v[22:23], s[14:15] op_sel_hi:[1,0]
	v_pk_mul_f32 v[54:55], v[20:21], s[14:15] op_sel_hi:[1,0]
	v_pk_mul_f32 v[18:19], v[42:43], s[14:15] op_sel_hi:[1,0]
	v_pk_mul_f32 v[22:23], v[40:41], s[14:15] op_sel_hi:[1,0]
	v_pk_mul_f32 v[16:17], v[46:47], s[14:15] op_sel_hi:[1,0]
	v_pk_mul_f32 v[20:21], v[44:45], s[14:15] op_sel_hi:[1,0]
	v_pk_mul_f32 v[40:41], v[10:11], s[14:15] op_sel_hi:[1,0]
	v_pk_mul_f32 v[44:45], v[8:9], s[14:15] op_sel_hi:[1,0]
	v_pk_mul_f32 v[34:35], v[14:15], s[14:15] op_sel_hi:[1,0]
	v_pk_mul_f32 v[42:43], v[12:13], s[14:15] op_sel_hi:[1,0]
	v_pk_mul_f32 v[10:11], v[26:27], s[14:15] op_sel_hi:[1,0]
	v_pk_mul_f32 v[14:15], v[24:25], s[14:15] op_sel_hi:[1,0]
	v_pk_mul_f32 v[8:9], v[30:31], s[14:15] op_sel_hi:[1,0]
	v_pk_mul_f32 v[12:13], v[28:29], s[14:15] op_sel_hi:[1,0]
	v_pk_mul_f32 v[2:3], v[2:3], s[14:15] op_sel_hi:[1,0]
	v_pk_mul_f32 v[24:25], v[0:1], s[14:15] op_sel_hi:[1,0]
	v_pk_mul_f32 v[0:1], v[6:7], s[14:15] op_sel_hi:[1,0]
	v_pk_mul_f32 v[4:5], v[4:5], s[14:15] op_sel_hi:[1,0]
	s_and_b64 vcc, exec, s[12:13]
	s_cbranch_vccz .LBB0_575

; #define PG8_STAGE(bufoff, gbase, voff) do { _Pragma("unroll") for (int _i = 0; _i < 2; ++_i) \
;         __builtin_amdgcn_global_load_lds((const unsigned*)((const char*)(gbase) + (voff)[_i]), (LAS unsigned*)(lds + (bufoff) + ldsw + _i * 8192), 16, 0, 0); } while (0)
; #define PG8_LDA(dst, b, h) do { _Pragma("unroll") for (int m = 0; m < 4; ++m) _Pragma("unroll") for (int k = 0; k < 2; ++k) dst[m][k] = *(const LAS bf16x8*)(lds + PG8_SA(b, h) + aoff + m * 2048 + k * KOFF); } while (0)
; #define PG8_LDB(dst, b, h) do { _Pragma("unroll") for (int n = 0; n < 2; ++n) _Pragma("unroll") for (int k = 0; k < 2; ++k) dst[n][k] = *(const LAS bf16x8*)(lds + PG8_SB(b, h) + boff + n * 2048 + k * KOFF); } while (0)
; #define PG8_WAIT_V(n) asm volatile("s_waitcnt vmcnt(" #n ")" ::: "memory")
; #define PG8_WAIT_L(n) asm volatile("s_waitcnt lgkmcnt(" #n ")" ::: "memory")
; #define PG8_BAR __builtin_amdgcn_s_barrier()
; #define PG8_SCHED __builtin_amdgcn_sched_barrier(0)
; template <class Epi, bool ALIGN_EPI = true, bool FP8 = false>
; __device__ __forceinline__ void gemm_phase(LAS unsigned char* lds, const Gemm g, const StaticOrder& S, const Epi& E, const int wid) {
;     ...
;             const char* a1 = cA + (size_t)(t + 1) * kstep;
;             const char* a2 = last ? nA : cA + (size_t)(t + 2) * kstep; const char* b2 = last ? nB : cB + (size_t)(t + 2) * kstep;
;             const char* a3 = a2 + kstep; const char* b3 = b2 + kstep;
;             PG8_LDB(B0, 0, 0); PG8_LDB(B1, 0, 1); PG8_SCHED; PG8_LDA(At, 0, 0); PG8_STAGE(PG8_SA(1, 1), a1 + hstep, voffA);
;             PG8_WAIT_V(8); PG8_WAIT_L(0); PG8_BAR; PG8_MMA(0, 0, At, B0); PG8_MMA(0, 1, At, B1); PG8_BAR; PG8_SCHED;
;             PG8_LDA(At, 0, 1); PG8_STAGE(PG8_SB(0, 0), b2, voffB); PG8_STAGE(PG8_SB(0, 1), b2 + hstep, voffB); PG8_STAGE(PG8_SA(0, 0), a2, voffA);
;             PG8_WAIT_V(8); PG8_WAIT_L(0); PG8_BAR; PG8_MMA(1, 0, At, B0); PG8_MMA(1, 1, At, B1); PG8_BAR; PG8_SCHED;
.LBB0_2058:
	v_add_u32_e32 v128, s83, v192
	v_add_u32_e32 v132, s84, v192
	ds_read_b128 v[152:155], v128
	ds_read_b128 v[156:159], v128 offset:1024
	ds_read_b128 v[144:147], v128 offset:2048
	ds_read_b128 v[148:151], v128 offset:3072
	ds_read_b128 v[136:139], v132
	ds_read_b128 v[140:143], v132 offset:1024
	ds_read_b128 v[128:131], v132 offset:2048
	ds_read_b128 v[132:135], v132 offset:3072
	s_add_i32 s3, s42, 2
	s_add_u32 s43, s64, 0xfffe0080
	s_addc_u32 s52, s65, -1
	s_cmp_eq_u32 s35, s42
	s_cselect_b32 s69, s11, s52
	s_cselect_b32 s68, s16, s43
	s_cselect_b32 s67, s29, s90
	s_cselect_b32 s66, s31, s89
	v_lshl_add_u64 v[188:189], s[64:65], 0, v[174:175]
	s_add_i32 m0, s72, 0xc000
	ds_read_b128 v[180:183], v193
	ds_read_b128 v[184:187], v193 offset:1024
	ds_read_b128 v[196:199], v193 offset:2048
	ds_read_b128 v[200:203], v193 offset:3072
	ds_read_b128 v[204:207], v193 offset:4096
	ds_read_b128 v[208:211], v193 offset:5120
	ds_read_b128 v[212:215], v193 offset:6144
	ds_read_b128 v[216:219], v193 offset:7168
	global_load_lds_dwordx4 v[188:189], off
	v_lshl_add_u64 v[188:189], s[64:65], 0, v[176:177]
	s_add_i32 m0, s72, 0xe000
	s_nop 0
	global_load_lds_dwordx4 v[188:189], off
	s_waitcnt vmcnt(8)
	s_waitcnt lgkmcnt(0)
	s_setprio 1
	s_barrier
	v_mfma_f32_16x16x128_f8f6f4 v[120:123], v[152:159], v[180:187], v[120:123]
	v_mfma_f32_16x16x128_f8f6f4 v[124:127], v[144:151], v[180:187], v[124:127]
	v_mfma_f32_16x16x128_f8f6f4 v[112:115], v[152:159], v[196:203], v[112:115]
	v_mfma_f32_16x16x128_f8f6f4 v[116:119], v[144:151], v[196:203], v[116:119]
	v_mfma_f32_16x16x128_f8f6f4 v[104:107], v[152:159], v[204:211], v[104:107]
	v_mfma_f32_16x16x128_f8f6f4 v[108:111], v[144:151], v[204:211], v[108:111]
	v_mfma_f32_16x16x128_f8f6f4 v[96:99], v[152:159], v[212:219], v[96:99]
	v_mfma_f32_16x16x128_f8f6f4 v[100:103], v[144:151], v[212:219], v[100:103]
	v_mfma_f32_16x16x128_f8f6f4 v[88:91], v[136:143], v[180:187], v[88:91]
	v_mfma_f32_16x16x128_f8f6f4 v[92:95], v[128:135], v[180:187], v[92:95]
	v_mfma_f32_16x16x128_f8f6f4 v[80:83], v[136:143], v[196:203], v[80:83]
	v_mfma_f32_16x16x128_f8f6f4 v[84:87], v[128:135], v[196:203], v[84:87]
	v_mfma_f32_16x16x128_f8f6f4 v[72:75], v[136:143], v[204:211], v[72:75]
	v_mfma_f32_16x16x128_f8f6f4 v[76:79], v[128:135], v[204:211], v[76:79]
	v_mfma_f32_16x16x128_f8f6f4 v[64:67], v[136:143], v[212:219], v[64:67]
	v_mfma_f32_16x16x128_f8f6f4 v[68:71], v[128:135], v[212:219], v[68:71]
	s_barrier
	s_setprio 0
	s_add_i32 s42, s83, s71
	v_lshl_add_u64 v[180:181], s[66:67], 0, v[162:163]
	s_mov_b32 m0, s42
	ds_read_b128 v[196:199], v193 offset:16384
	ds_read_b128 v[200:203], v193 offset:17408
	ds_read_b128 v[204:207], v193 offset:18432
	ds_read_b128 v[208:211], v193 offset:19456
	ds_read_b128 v[212:215], v193 offset:20480
	ds_read_b128 v[216:219], v193 offset:21504
	ds_read_b128 v[220:223], v193 offset:22528
	ds_read_b128 v[224:227], v193 offset:23552
	global_load_lds_dwordx4 v[180:181], off
	s_add_i32 m0, s42, 0x2000
	s_add_u32 s42, s66, 0x20000
	v_lshl_add_u64 v[182:183], s[66:67], 0, v[166:167]
	s_addc_u32 s43, s67, 0
	s_add_i32 s52, s84, s71
	global_load_lds_dwordx4 v[182:183], off
	v_lshl_add_u64 v[184:185], s[42:43], 0, v[162:163]
	s_mov_b32 m0, s52
	v_lshl_add_u64 v[186:187], s[68:69], 0, v[164:165]
	global_load_lds_dwordx4 v[184:185], off
	v_lshl_add_u64 v[184:185], s[42:43], 0, v[166:167]
	s_add_i32 m0, s52, 0x2000
	s_nop 0
	global_load_lds_dwordx4 v[184:185], off
	v_lshl_add_u64 v[184:185], s[68:69], 0, v[160:161]
	s_mov_b32 m0, s72
	s_nop 0
	global_load_lds_dwordx4 v[184:185], off
	s_mov_b32 m0, s73
	s_nop 0
	global_load_lds_dwordx4 v[186:187], off
	s_waitcnt vmcnt(8)
	s_waitcnt lgkmcnt(0)
	s_setprio 1
	s_barrier
	v_mfma_f32_16x16x128_f8f6f4 v[56:59], v[152:159], v[196:203], v[56:59]
	v_mfma_f32_16x16x128_f8f6f4 v[60:63], v[144:151], v[196:203], v[60:63]
	v_mfma_f32_16x16x128_f8f6f4 v[48:51], v[152:159], v[204:211], v[48:51]
	v_mfma_f32_16x16x128_f8f6f4 v[52:55], v[144:151], v[204:211], v[52:55]
	v_mfma_f32_16x16x128_f8f6f4 v[40:43], v[152:159], v[212:219], v[40:43]
	v_mfma_f32_16x16x128_f8f6f4 v[44:47], v[144:151], v[212:219], v[44:47]
	v_mfma_f32_16x16x128_f8f6f4 v[188:191], v[152:159], v[220:227], v[32:35]
	v_mfma_f32_16x16x128_f8f6f4 v[228:231], v[144:151], v[220:227], v[36:39]
	v_mfma_f32_16x16x128_f8f6f4 v[232:235], v[136:143], v[196:203], v[24:27]
	v_mfma_f32_16x16x128_f8f6f4 v[236:239], v[128:135], v[196:203], v[28:31]
	v_mfma_f32_16x16x128_f8f6f4 v[240:243], v[136:143], v[204:211], v[16:19]
	v_mfma_f32_16x16x128_f8f6f4 v[204:207], v[128:135], v[204:211], v[20:23]
	v_mfma_f32_16x16x128_f8f6f4 v[208:211], v[136:143], v[212:219], v[8:11]
	v_mfma_f32_16x16x128_f8f6f4 v[212:215], v[128:135], v[212:219], v[12:15]
	v_mfma_f32_16x16x128_f8f6f4 v[216:219], v[136:143], v[220:227], v[0:3]
	v_mfma_f32_16x16x128_f8f6f4 v[220:223], v[128:135], v[220:227], v[4:7]
	s_barrier
; #define PG8_STAGE(bufoff, gbase, voff) do { _Pragma("unroll") for (int _i = 0; _i < 2; ++_i) \
;         __builtin_amdgcn_global_load_lds((const unsigned*)((const char*)(gbase) + (voff)[_i]), (LAS unsigned*)(lds + (bufoff) + ldsw + _i * 8192), 16, 0, 0); } while (0)
; #define PG8_LDA(dst, b, h) do { _Pragma("unroll") for (int m = 0; m < 4; ++m) _Pragma("unroll") for (int k = 0; k < 2; ++k) dst[m][k] = *(const LAS bf16x8*)(lds + PG8_SA(b, h) + aoff + m * 2048 + k * KOFF); } while (0)
; #define PG8_LDB(dst, b, h) do { _Pragma("unroll") for (int n = 0; n < 2; ++n) _Pragma("unroll") for (int k = 0; k < 2; ++k) dst[n][k] = *(const LAS bf16x8*)(lds + PG8_SB(b, h) + boff + n * 2048 + k * KOFF); } while (0)
; #define PG8_WAIT_V(n) asm volatile("s_waitcnt vmcnt(" #n ")" ::: "memory")
; #define PG8_WAIT_L(n) asm volatile("s_waitcnt lgkmcnt(" #n ")" ::: "memory")
; #define PG8_BAR __builtin_amdgcn_s_barrier()
; #define PG8_SCHED __builtin_amdgcn_sched_barrier(0)
; template <class Epi, bool ALIGN_EPI = true, bool FP8 = false>
; __device__ __forceinline__ void gemm_phase(LAS unsigned char* lds, const Gemm g, const StaticOrder& S, const Epi& E, const int wid) {
;     ...
;             PG8_LDB(B0, 1, 0); PG8_LDB(B1, 1, 1); PG8_SCHED; PG8_LDA(At, 1, 0); PG8_STAGE(PG8_SA(0, 1), a2 + hstep, voffA);
;             PG8_WAIT_V(8); PG8_WAIT_L(0); PG8_BAR; PG8_MMA(0, 0, At, B0); PG8_MMA(0, 1, At, B1); PG8_BAR; PG8_SCHED;
;             PG8_LDA(At, 1, 1); PG8_STAGE(PG8_SB(1, 0), b3, voffB); PG8_STAGE(PG8_SB(1, 1), b3 + hstep, voffB); PG8_STAGE(PG8_SA(1, 0), a3, voffA);
;             PG8_WAIT_V(8); PG8_WAIT_L(0); PG8_BAR; PG8_MMA(1, 0, At, B0); PG8_MMA(1, 1, At, B1); PG8_BAR; PG8_SCHED;
;         }
;         if constexpr (ALIGN_EPI) { if (wr == 0) PG8_BAR; }
	s_setprio 0
	s_add_i32 s52, 0, 0x18000
	s_add_i32 s54, 0, 0x1c000
	s_nop 0
	v_add_u32_e32 v12, s52, v192
	v_add_u32_e32 v16, s54, v192
	ds_read_b128 v[0:3], v12
	ds_read_b128 v[4:7], v12 offset:1024
	ds_read_b128 v[8:11], v12 offset:2048
	ds_read_b128 v[12:15], v12 offset:3072
	ds_read_b128 v[128:131], v16
	ds_read_b128 v[132:135], v16 offset:1024
	ds_read_b128 v[136:139], v16 offset:2048
	ds_read_b128 v[140:143], v16 offset:3072
	s_add_u32 s42, s68, 0x20000
	s_addc_u32 s43, s69, 0
	s_mov_b32 m0, s74
	v_lshl_add_u64 v[152:153], s[42:43], 0, v[160:161]
	ds_read_b128 v[16:19], v193 offset:32768
	ds_read_b128 v[20:23], v193 offset:33792
	ds_read_b128 v[24:27], v193 offset:34816
	ds_read_b128 v[28:31], v193 offset:35840
	ds_read_b128 v[32:35], v193 offset:36864
	ds_read_b128 v[36:39], v193 offset:37888
	ds_read_b128 v[144:147], v193 offset:38912
	ds_read_b128 v[148:151], v193 offset:39936
	global_load_lds_dwordx4 v[152:153], off
	v_lshl_add_u64 v[152:153], s[42:43], 0, v[164:165]
	s_mov_b32 m0, s75
	s_nop 0
	global_load_lds_dwordx4 v[152:153], off
	s_waitcnt vmcnt(8)
	s_waitcnt lgkmcnt(0)
	s_setprio 1
	s_barrier
	v_mfma_f32_16x16x128_f8f6f4 v[120:123], v[0:7], v[16:23], v[120:123]
	v_mfma_f32_16x16x128_f8f6f4 v[124:127], v[8:15], v[16:23], v[124:127]
	v_mfma_f32_16x16x128_f8f6f4 v[112:115], v[0:7], v[24:31], v[112:115]
	v_mfma_f32_16x16x128_f8f6f4 v[116:119], v[8:15], v[24:31], v[116:119]
	v_mfma_f32_16x16x128_f8f6f4 v[104:107], v[0:7], v[32:39], v[104:107]
	v_mfma_f32_16x16x128_f8f6f4 v[108:111], v[8:15], v[32:39], v[108:111]
	v_mfma_f32_16x16x128_f8f6f4 v[96:99], v[0:7], v[144:151], v[96:99]
	v_mfma_f32_16x16x128_f8f6f4 v[100:103], v[8:15], v[144:151], v[100:103]
	v_mfma_f32_16x16x128_f8f6f4 v[88:91], v[128:135], v[16:23], v[88:91]
	v_mfma_f32_16x16x128_f8f6f4 v[92:95], v[136:143], v[16:23], v[92:95]
	v_mfma_f32_16x16x128_f8f6f4 v[80:83], v[128:135], v[24:31], v[80:83]
	v_mfma_f32_16x16x128_f8f6f4 v[84:87], v[136:143], v[24:31], v[84:87]
	v_mfma_f32_16x16x128_f8f6f4 v[72:75], v[128:135], v[32:39], v[72:75]
	v_mfma_f32_16x16x128_f8f6f4 v[76:79], v[136:143], v[32:39], v[76:79]
	v_mfma_f32_16x16x128_f8f6f4 v[64:67], v[128:135], v[144:151], v[64:67]
	v_mfma_f32_16x16x128_f8f6f4 v[68:71], v[136:143], v[144:151], v[68:71]
	s_barrier
	s_setprio 0
	s_add_i32 s42, s52, s71
	v_lshl_add_u64 v[24:25], v[180:181], 0, s[20:21]
	s_mov_b32 m0, s42
	ds_read_b128 v[16:19], v193 offset:49152
	ds_read_b128 v[20:23], v193 offset:50176
	ds_read_b128 v[144:147], v193 offset:51200
	ds_read_b128 v[148:151], v193 offset:52224
	ds_read_b128 v[152:155], v193 offset:53248
	ds_read_b128 v[156:159], v193 offset:54272
	ds_read_b128 v[196:199], v193 offset:55296
	ds_read_b128 v[200:203], v193 offset:56320
	global_load_lds_dwordx4 v[24:25], off
	s_add_i32 m0, s42, 0x2000
	s_add_u32 s42, s66, 0x20080
	v_lshl_add_u64 v[24:25], v[182:183], 0, s[20:21]
	s_addc_u32 s43, s67, 0
	s_add_i32 s52, s54, s71
	global_load_lds_dwordx4 v[24:25], off
	v_lshl_add_u64 v[24:25], s[42:43], 0, v[162:163]
	s_mov_b32 m0, s52
	s_nop 0
	global_load_lds_dwordx4 v[24:25], off
	v_lshl_add_u64 v[24:25], s[42:43], 0, v[166:167]
	s_add_i32 m0, s52, 0x2000
	s_nop 0
	global_load_lds_dwordx4 v[24:25], off
	v_lshl_add_u64 v[24:25], v[184:185], 0, s[20:21]
	s_mov_b32 m0, s80
	s_nop 0
	global_load_lds_dwordx4 v[24:25], off
	v_lshl_add_u64 v[24:25], v[186:187], 0, s[20:21]
	s_mov_b32 m0, s81
	s_nop 0
	global_load_lds_dwordx4 v[24:25], off
	s_waitcnt vmcnt(8)
	s_waitcnt lgkmcnt(0)
	s_setprio 1
	s_barrier
	v_mfma_f32_16x16x128_f8f6f4 v[56:59], v[0:7], v[16:23], v[56:59]
	v_mfma_f32_16x16x128_f8f6f4 v[60:63], v[8:15], v[16:23], v[60:63]
	v_mfma_f32_16x16x128_f8f6f4 v[48:51], v[0:7], v[144:151], v[48:51]
	v_mfma_f32_16x16x128_f8f6f4 v[52:55], v[8:15], v[144:151], v[52:55]
	v_mfma_f32_16x16x128_f8f6f4 v[40:43], v[0:7], v[152:159], v[40:43]
	v_mfma_f32_16x16x128_f8f6f4 v[44:47], v[8:15], v[152:159], v[44:47]
	v_mfma_f32_16x16x128_f8f6f4 v[32:35], v[0:7], v[196:203], v[188:191]
	v_mfma_f32_16x16x128_f8f6f4 v[36:39], v[8:15], v[196:203], v[228:231]
	v_mfma_f32_16x16x128_f8f6f4 v[24:27], v[128:135], v[16:23], v[232:235]
	v_mfma_f32_16x16x128_f8f6f4 v[28:31], v[136:143], v[16:23], v[236:239]
	v_mfma_f32_16x16x128_f8f6f4 v[16:19], v[128:135], v[144:151], v[240:243]
	v_mfma_f32_16x16x128_f8f6f4 v[20:23], v[136:143], v[144:151], v[204:207]
	v_mfma_f32_16x16x128_f8f6f4 v[8:11], v[128:135], v[152:159], v[208:211]
	v_mfma_f32_16x16x128_f8f6f4 v[12:15], v[136:143], v[152:159], v[212:215]
	v_mfma_f32_16x16x128_f8f6f4 v[0:3], v[128:135], v[196:203], v[216:219]
	v_mfma_f32_16x16x128_f8f6f4 v[4:7], v[136:143], v[196:203], v[220:223]
	s_barrier
	s_setprio 0
	s_add_u32 s64, s64, 0x100
	s_addc_u32 s65, s65, 0
	s_add_u32 s89, s89, 0x100
	s_addc_u32 s90, s90, 0
	s_cmp_ge_u32 s3, s9
	s_mov_b32 s42, s3
	s_cbranch_scc0 .LBB0_2058
	s_and_b64 vcc, exec, s[22:23]
	s_cbranch_vccz .LBB0_2061
	s_barrier

; #define PG8_STAGE(bufoff, gbase, voff) do { _Pragma("unroll") for (int _i = 0; _i < 2; ++_i) \
;         __builtin_amdgcn_global_load_lds((const unsigned*)((const char*)(gbase) + (voff)[_i]), (LAS unsigned*)(lds + (bufoff) + ldsw + _i * 8192), 16, 0, 0); } while (0)
; #define PG8_LDA(dst, b, h) do { _Pragma("unroll") for (int m = 0; m < 4; ++m) _Pragma("unroll") for (int k = 0; k < 2; ++k) dst[m][k] = *(const LAS bf16x8*)(lds + PG8_SA(b, h) + aoff + m * 2048 + k * KOFF); } while (0)
; #define PG8_LDB(dst, b, h) do { _Pragma("unroll") for (int n = 0; n < 2; ++n) _Pragma("unroll") for (int k = 0; k < 2; ++k) dst[n][k] = *(const LAS bf16x8*)(lds + PG8_SB(b, h) + boff + n * 2048 + k * KOFF); } while (0)
; #define PG8_WAIT_V(n) asm volatile("s_waitcnt vmcnt(" #n ")" ::: "memory")
; #define PG8_WAIT_L(n) asm volatile("s_waitcnt lgkmcnt(" #n ")" ::: "memory")
; #define PG8_BAR __builtin_amdgcn_s_barrier()
; #define PG8_SCHED __builtin_amdgcn_sched_barrier(0)
; template <class Epi, bool ALIGN_EPI = true, bool FP8 = false>
; __device__ __forceinline__ void gemm_phase(LAS unsigned char* lds, const Gemm g, const StaticOrder& S, const Epi& E, const int wid) {
;     ...
;             const char* a1 = cA + (size_t)(t + 1) * kstep;
;             const char* a2 = last ? nA : cA + (size_t)(t + 2) * kstep; const char* b2 = last ? nB : cB + (size_t)(t + 2) * kstep;
;             const char* a3 = a2 + kstep; const char* b3 = b2 + kstep;
;             PG8_LDB(B0, 0, 0); PG8_LDB(B1, 0, 1); PG8_SCHED; PG8_LDA(At, 0, 0); PG8_STAGE(PG8_SA(1, 1), a1 + hstep, voffA);
;             PG8_WAIT_V(8); PG8_WAIT_L(0); PG8_BAR; PG8_MMA(0, 0, At, B0); PG8_MMA(0, 1, At, B1); PG8_BAR; PG8_SCHED;
;             PG8_LDA(At, 0, 1); PG8_STAGE(PG8_SB(0, 0), b2, voffB); PG8_STAGE(PG8_SB(0, 1), b2 + hstep, voffB); PG8_STAGE(PG8_SA(0, 0), a2, voffA);
;             PG8_WAIT_V(8); PG8_WAIT_L(0); PG8_BAR; PG8_MMA(1, 0, At, B0); PG8_MMA(1, 1, At, B1); PG8_BAR; PG8_SCHED;
.LBB0_2290:
	ds_read_b128 v[152:155], v218
	ds_read_b128 v[156:159], v218 offset:1024
	ds_read_b128 v[144:147], v218 offset:2048
	ds_read_b128 v[148:151], v218 offset:3072
	ds_read_b128 v[136:139], v219
	ds_read_b128 v[140:143], v219 offset:1024
	ds_read_b128 v[128:131], v219 offset:2048
	ds_read_b128 v[132:135], v219 offset:3072
	s_add_i32 s3, s38, 2
	s_add_u32 s36, s34, 0xfffc0080
	s_addc_u32 s37, s35, -1
	s_cmp_eq_u32 s88, s38
	s_cselect_b32 s38, s31, s36
	s_cselect_b32 s39, s21, s37
	s_cselect_b32 s37, s19, s90
	s_cselect_b32 s36, s87, s89
	v_lshl_add_u64 v[212:213], s[34:35], 0, v[198:199]
	s_add_i32 m0, s27, 0xc000
	ds_read_b128 v[160:163], v220
	ds_read_b128 v[164:167], v220 offset:1024
	ds_read_b128 v[168:171], v220 offset:2048
	ds_read_b128 v[172:175], v220 offset:3072
	ds_read_b128 v[176:179], v220 offset:4096
	ds_read_b128 v[180:183], v220 offset:5120
	ds_read_b128 v[204:207], v220 offset:6144
	ds_read_b128 v[208:211], v220 offset:7168
	global_load_lds_dwordx4 v[212:213], off
	v_lshl_add_u64 v[212:213], s[34:35], 0, v[200:201]
	s_add_i32 m0, s27, 0xe000
	s_nop 0
	global_load_lds_dwordx4 v[212:213], off
	s_waitcnt vmcnt(8)
	s_waitcnt lgkmcnt(0)
	s_setprio 1
	s_barrier
	v_mfma_f32_16x16x128_f8f6f4 v[120:123], v[152:159], v[160:167], v[120:123]
	v_mfma_f32_16x16x128_f8f6f4 v[124:127], v[144:151], v[160:167], v[124:127]
	v_mfma_f32_16x16x128_f8f6f4 v[104:107], v[152:159], v[168:175], v[104:107]
	v_mfma_f32_16x16x128_f8f6f4 v[108:111], v[144:151], v[168:175], v[108:111]
	v_mfma_f32_16x16x128_f8f6f4 v[96:99], v[152:159], v[176:183], v[96:99]
	v_mfma_f32_16x16x128_f8f6f4 v[100:103], v[144:151], v[176:183], v[100:103]
	v_mfma_f32_16x16x128_f8f6f4 v[80:83], v[152:159], v[204:211], v[80:83]
	v_mfma_f32_16x16x128_f8f6f4 v[84:87], v[144:151], v[204:211], v[84:87]
	v_mfma_f32_16x16x128_f8f6f4 v[112:115], v[136:143], v[160:167], v[112:115]
	v_mfma_f32_16x16x128_f8f6f4 v[116:119], v[128:135], v[160:167], v[116:119]
	v_mfma_f32_16x16x128_f8f6f4 v[88:91], v[136:143], v[168:175], v[88:91]
	v_mfma_f32_16x16x128_f8f6f4 v[92:95], v[128:135], v[168:175], v[92:95]
	v_mfma_f32_16x16x128_f8f6f4 v[72:75], v[136:143], v[176:183], v[72:75]
	v_mfma_f32_16x16x128_f8f6f4 v[76:79], v[128:135], v[176:183], v[76:79]
	v_mfma_f32_16x16x128_f8f6f4 v[64:67], v[136:143], v[204:211], v[64:67]
	v_mfma_f32_16x16x128_f8f6f4 v[68:71], v[128:135], v[204:211], v[68:71]
	s_barrier
	s_setprio 0
	s_add_i32 s42, s75, s53
	v_lshl_add_u64 v[160:161], s[36:37], 0, v[188:189]
	s_mov_b32 m0, s42
	ds_read_b128 v[168:171], v220 offset:16384
	ds_read_b128 v[172:175], v220 offset:17408
	ds_read_b128 v[176:179], v220 offset:18432
	ds_read_b128 v[180:183], v220 offset:19456
	ds_read_b128 v[204:207], v220 offset:20480
	ds_read_b128 v[208:211], v220 offset:21504
	ds_read_b128 v[222:225], v220 offset:22528
	ds_read_b128 v[226:229], v220 offset:23552
	global_load_lds_dwordx4 v[160:161], off
	s_add_i32 m0, s42, 0x2000
	s_add_u32 s42, s36, 0x40000
	v_lshl_add_u64 v[162:163], s[36:37], 0, v[184:185]
	s_addc_u32 s43, s37, 0
	s_add_i32 s52, s76, s53
	global_load_lds_dwordx4 v[162:163], off
	v_lshl_add_u64 v[164:165], s[42:43], 0, v[188:189]
	s_mov_b32 m0, s52
	v_lshl_add_u64 v[166:167], s[38:39], 0, v[186:187]
	global_load_lds_dwordx4 v[164:165], off
	v_lshl_add_u64 v[164:165], s[42:43], 0, v[184:185]
	s_add_i32 m0, s52, 0x2000
	s_nop 0
	global_load_lds_dwordx4 v[164:165], off
	v_lshl_add_u64 v[164:165], s[38:39], 0, v[190:191]
	s_mov_b32 m0, s27
	s_nop 0
	global_load_lds_dwordx4 v[164:165], off
	s_mov_b32 m0, s55
	s_nop 0
	global_load_lds_dwordx4 v[166:167], off
	s_waitcnt vmcnt(8)
	s_waitcnt lgkmcnt(0)
	s_setprio 1
	s_barrier
	v_mfma_f32_16x16x128_f8f6f4 v[56:59], v[152:159], v[168:175], v[56:59]
	v_mfma_f32_16x16x128_f8f6f4 v[60:63], v[144:151], v[168:175], v[60:63]
	v_mfma_f32_16x16x128_f8f6f4 v[48:51], v[152:159], v[176:183], v[48:51]
	v_mfma_f32_16x16x128_f8f6f4 v[52:55], v[144:151], v[176:183], v[52:55]
	v_mfma_f32_16x16x128_f8f6f4 v[32:35], v[152:159], v[204:211], v[32:35]
	v_mfma_f32_16x16x128_f8f6f4 v[212:215], v[144:151], v[204:211], v[36:39]
	v_mfma_f32_16x16x128_f8f6f4 v[230:233], v[152:159], v[222:229], v[16:19]
	v_mfma_f32_16x16x128_f8f6f4 v[234:237], v[144:151], v[222:229], v[20:23]
	v_mfma_f32_16x16x128_f8f6f4 v[44:47], v[128:135], v[168:175], v[44:47]
	v_mfma_f32_16x16x128_f8f6f4 v[238:241], v[136:143], v[168:175], v[40:43]
	v_mfma_f32_16x16x128_f8f6f4 v[242:245], v[136:143], v[176:183], v[24:27]
	v_mfma_f32_16x16x128_f8f6f4 v[176:179], v[128:135], v[176:183], v[28:31]
	v_mfma_f32_16x16x128_f8f6f4 v[180:183], v[136:143], v[204:211], v[8:11]
	v_mfma_f32_16x16x128_f8f6f4 v[204:207], v[128:135], v[204:211], v[12:15]
	v_mfma_f32_16x16x128_f8f6f4 v[208:211], v[136:143], v[222:229], v[0:3]
	v_mfma_f32_16x16x128_f8f6f4 v[222:225], v[128:135], v[222:229], v[4:7]
	s_barrier
; #define PG8_STAGE(bufoff, gbase, voff) do { _Pragma("unroll") for (int _i = 0; _i < 2; ++_i) \
;         __builtin_amdgcn_global_load_lds((const unsigned*)((const char*)(gbase) + (voff)[_i]), (LAS unsigned*)(lds + (bufoff) + ldsw + _i * 8192), 16, 0, 0); } while (0)
; #define PG8_LDA(dst, b, h) do { _Pragma("unroll") for (int m = 0; m < 4; ++m) _Pragma("unroll") for (int k = 0; k < 2; ++k) dst[m][k] = *(const LAS bf16x8*)(lds + PG8_SA(b, h) + aoff + m * 2048 + k * KOFF); } while (0)
; #define PG8_LDB(dst, b, h) do { _Pragma("unroll") for (int n = 0; n < 2; ++n) _Pragma("unroll") for (int k = 0; k < 2; ++k) dst[n][k] = *(const LAS bf16x8*)(lds + PG8_SB(b, h) + boff + n * 2048 + k * KOFF); } while (0)
; #define PG8_WAIT_V(n) asm volatile("s_waitcnt vmcnt(" #n ")" ::: "memory")
; #define PG8_WAIT_L(n) asm volatile("s_waitcnt lgkmcnt(" #n ")" ::: "memory")
; #define PG8_BAR __builtin_amdgcn_s_barrier()
; #define PG8_SCHED __builtin_amdgcn_sched_barrier(0)
; template <class Epi, bool ALIGN_EPI = true, bool FP8 = false>
; __device__ __forceinline__ void gemm_phase(LAS unsigned char* lds, const Gemm g, const StaticOrder& S, const Epi& E, const int wid) {
;     ...
;             PG8_LDB(B0, 1, 0); PG8_LDB(B1, 1, 1); PG8_SCHED; PG8_LDA(At, 1, 0); PG8_STAGE(PG8_SA(0, 1), a2 + hstep, voffA);
;             PG8_WAIT_V(8); PG8_WAIT_L(0); PG8_BAR; PG8_MMA(0, 0, At, B0); PG8_MMA(0, 1, At, B1); PG8_BAR; PG8_SCHED;
;             PG8_LDA(At, 1, 1); PG8_STAGE(PG8_SB(1, 0), b3, voffB); PG8_STAGE(PG8_SB(1, 1), b3 + hstep, voffB); PG8_STAGE(PG8_SA(1, 0), a3, voffA);
;             PG8_WAIT_V(8); PG8_WAIT_L(0); PG8_BAR; PG8_MMA(1, 0, At, B0); PG8_MMA(1, 1, At, B1); PG8_BAR; PG8_SCHED;
;         }
;         if constexpr (ALIGN_EPI) { if (wr == 0) PG8_BAR; }
	s_setprio 0
	s_add_i32 s42, 0, 0x18000
	s_add_i32 s43, 0, 0x1c000
	s_nop 0
	v_add_u32_e32 v12, s42, v217
	v_add_u32_e32 v16, s43, v217
	ds_read_b128 v[0:3], v12
	ds_read_b128 v[4:7], v12 offset:1024
	ds_read_b128 v[8:11], v12 offset:2048
	ds_read_b128 v[12:15], v12 offset:3072
	ds_read_b128 v[128:131], v16
	ds_read_b128 v[132:135], v16 offset:1024
	ds_read_b128 v[136:139], v16 offset:2048
	ds_read_b128 v[140:143], v16 offset:3072
	s_add_u32 s38, s38, 0x40000
	s_addc_u32 s39, s39, 0
	s_mov_b32 m0, s64
	v_lshl_add_u64 v[152:153], s[38:39], 0, v[190:191]
	ds_read_b128 v[16:19], v220 offset:32768
	ds_read_b128 v[20:23], v220 offset:33792
	ds_read_b128 v[24:27], v220 offset:34816
	ds_read_b128 v[28:31], v220 offset:35840
	ds_read_b128 v[36:39], v220 offset:36864
	ds_read_b128 v[40:43], v220 offset:37888
	ds_read_b128 v[144:147], v220 offset:38912
	ds_read_b128 v[148:151], v220 offset:39936
	global_load_lds_dwordx4 v[152:153], off
	v_lshl_add_u64 v[152:153], s[38:39], 0, v[186:187]
	s_mov_b32 m0, s65
	s_nop 0
	global_load_lds_dwordx4 v[152:153], off
	s_waitcnt vmcnt(8)
	s_waitcnt lgkmcnt(0)
	s_setprio 1
	s_barrier
	v_mfma_f32_16x16x128_f8f6f4 v[120:123], v[0:7], v[16:23], v[120:123]
	v_mfma_f32_16x16x128_f8f6f4 v[124:127], v[8:15], v[16:23], v[124:127]
	v_mfma_f32_16x16x128_f8f6f4 v[104:107], v[0:7], v[24:31], v[104:107]
	v_mfma_f32_16x16x128_f8f6f4 v[108:111], v[8:15], v[24:31], v[108:111]
	v_mfma_f32_16x16x128_f8f6f4 v[96:99], v[0:7], v[36:43], v[96:99]
	v_mfma_f32_16x16x128_f8f6f4 v[100:103], v[8:15], v[36:43], v[100:103]
	v_mfma_f32_16x16x128_f8f6f4 v[80:83], v[0:7], v[144:151], v[80:83]
	v_mfma_f32_16x16x128_f8f6f4 v[84:87], v[8:15], v[144:151], v[84:87]
	v_mfma_f32_16x16x128_f8f6f4 v[112:115], v[128:135], v[16:23], v[112:115]
	v_mfma_f32_16x16x128_f8f6f4 v[116:119], v[136:143], v[16:23], v[116:119]
	v_mfma_f32_16x16x128_f8f6f4 v[88:91], v[128:135], v[24:31], v[88:91]
	v_mfma_f32_16x16x128_f8f6f4 v[92:95], v[136:143], v[24:31], v[92:95]
	v_mfma_f32_16x16x128_f8f6f4 v[72:75], v[128:135], v[36:43], v[72:75]
	v_mfma_f32_16x16x128_f8f6f4 v[76:79], v[136:143], v[36:43], v[76:79]
	v_mfma_f32_16x16x128_f8f6f4 v[64:67], v[128:135], v[144:151], v[64:67]
	v_mfma_f32_16x16x128_f8f6f4 v[68:71], v[136:143], v[144:151], v[68:71]
	s_barrier
	s_setprio 0
	s_add_i32 s38, s42, s53
	v_lshl_add_u64 v[16:17], v[160:161], 0, s[14:15]
	s_mov_b32 m0, s38
	ds_read_b128 v[24:27], v220 offset:49152
	ds_read_b128 v[28:31], v220 offset:50176
	ds_read_b128 v[144:147], v220 offset:51200
	ds_read_b128 v[148:151], v220 offset:52224
	ds_read_b128 v[152:155], v220 offset:53248
	ds_read_b128 v[156:159], v220 offset:54272
	ds_read_b128 v[168:171], v220 offset:55296
	ds_read_b128 v[172:175], v220 offset:56320
	global_load_lds_dwordx4 v[16:17], off
	s_add_i32 m0, s38, 0x2000
	s_add_u32 s36, s36, 0x40080
	v_lshl_add_u64 v[16:17], v[162:163], 0, s[14:15]
	s_addc_u32 s37, s37, 0
	s_add_i32 s38, s43, s53
	global_load_lds_dwordx4 v[16:17], off
	v_lshl_add_u64 v[16:17], s[36:37], 0, v[188:189]
	s_mov_b32 m0, s38
	s_nop 0
	global_load_lds_dwordx4 v[16:17], off
	v_lshl_add_u64 v[16:17], s[36:37], 0, v[184:185]
	s_add_i32 m0, s38, 0x2000
	s_nop 0
	global_load_lds_dwordx4 v[16:17], off
	v_lshl_add_u64 v[16:17], v[164:165], 0, s[14:15]
	s_mov_b32 m0, s71
	s_nop 0
	global_load_lds_dwordx4 v[16:17], off
	v_lshl_add_u64 v[16:17], v[166:167], 0, s[14:15]
	s_mov_b32 m0, s72
	s_nop 0
	global_load_lds_dwordx4 v[16:17], off
	s_waitcnt vmcnt(8)
	s_waitcnt lgkmcnt(0)
	s_setprio 1
	s_barrier
	v_mfma_f32_16x16x128_f8f6f4 v[56:59], v[0:7], v[24:31], v[56:59]
	v_mfma_f32_16x16x128_f8f6f4 v[60:63], v[8:15], v[24:31], v[60:63]
	v_mfma_f32_16x16x128_f8f6f4 v[48:51], v[0:7], v[144:151], v[48:51]
	v_mfma_f32_16x16x128_f8f6f4 v[52:55], v[8:15], v[144:151], v[52:55]
	v_mfma_f32_16x16x128_f8f6f4 v[32:35], v[0:7], v[152:159], v[32:35]
	v_mfma_f32_16x16x128_f8f6f4 v[36:39], v[8:15], v[152:159], v[212:215]
	v_mfma_f32_16x16x128_f8f6f4 v[16:19], v[0:7], v[168:175], v[230:233]
	v_mfma_f32_16x16x128_f8f6f4 v[20:23], v[8:15], v[168:175], v[234:237]
	v_mfma_f32_16x16x128_f8f6f4 v[40:43], v[128:135], v[24:31], v[238:241]
	v_mfma_f32_16x16x128_f8f6f4 v[44:47], v[136:143], v[24:31], v[44:47]
	v_mfma_f32_16x16x128_f8f6f4 v[24:27], v[128:135], v[144:151], v[242:245]
	v_mfma_f32_16x16x128_f8f6f4 v[28:31], v[136:143], v[144:151], v[176:179]
	v_mfma_f32_16x16x128_f8f6f4 v[8:11], v[128:135], v[152:159], v[180:183]
	v_mfma_f32_16x16x128_f8f6f4 v[12:15], v[136:143], v[152:159], v[204:207]
	v_mfma_f32_16x16x128_f8f6f4 v[0:3], v[128:135], v[168:175], v[208:211]
	v_mfma_f32_16x16x128_f8f6f4 v[4:7], v[136:143], v[168:175], v[222:225]
	s_barrier
	s_setprio 0
	s_add_u32 s34, s34, 0x100
	s_addc_u32 s35, s35, 0
	s_add_u32 s89, s89, 0x100
	s_addc_u32 s90, s90, 0
	s_cmp_ge_u32 s3, s29
	s_mov_b32 s38, s3
	s_cbranch_scc0 .LBB0_2290
	s_and_b64 vcc, exec, s[12:13]
	s_cbranch_vccz .LBB0_2293
	s_barrier

; #define PG8_STAGE(bufoff, gbase, voff) do { _Pragma("unroll") for (int _i = 0; _i < 2; ++_i) \
;         __builtin_amdgcn_global_load_lds((const unsigned*)((const char*)(gbase) + (voff)[_i]), (LAS unsigned*)(lds + (bufoff) + ldsw + _i * 8192), 16, 0, 0); } while (0)
; #define PG8_LDA(dst, b, h) do { _Pragma("unroll") for (int m = 0; m < 4; ++m) _Pragma("unroll") for (int k = 0; k < 2; ++k) dst[m][k] = *(const LAS bf16x8*)(lds + PG8_SA(b, h) + aoff + m * 2048 + k * KOFF); } while (0)
; #define PG8_LDB(dst, b, h) do { _Pragma("unroll") for (int n = 0; n < 2; ++n) _Pragma("unroll") for (int k = 0; k < 2; ++k) dst[n][k] = *(const LAS bf16x8*)(lds + PG8_SB(b, h) + boff + n * 2048 + k * KOFF); } while (0)
; #define PG8_WAIT_V(n) asm volatile("s_waitcnt vmcnt(" #n ")" ::: "memory")
; #define PG8_WAIT_L(n) asm volatile("s_waitcnt lgkmcnt(" #n ")" ::: "memory")
; #define PG8_BAR __builtin_amdgcn_s_barrier()
; #define PG8_SCHED __builtin_amdgcn_sched_barrier(0)
; template <class Epi, bool ALIGN_EPI = true, bool FP8 = false>
; __device__ __forceinline__ void gemm_phase(LAS unsigned char* lds, const Gemm g, const StaticOrder& S, const Epi& E, const int wid) {
;     ...
;             const char* a1 = cA + (size_t)(t + 1) * kstep;
;             const char* a2 = last ? nA : cA + (size_t)(t + 2) * kstep; const char* b2 = last ? nB : cB + (size_t)(t + 2) * kstep;
;             const char* a3 = a2 + kstep; const char* b3 = b2 + kstep;
;             PG8_LDB(B0, 0, 0); PG8_LDB(B1, 0, 1); PG8_SCHED; PG8_LDA(At, 0, 0); PG8_STAGE(PG8_SA(1, 1), a1 + hstep, voffA);
;             PG8_WAIT_V(8); PG8_WAIT_L(0); PG8_BAR; PG8_MMA(0, 0, At, B0); PG8_MMA(0, 1, At, B1); PG8_BAR; PG8_SCHED;
;             PG8_LDA(At, 0, 1); PG8_STAGE(PG8_SB(0, 0), b2, voffB); PG8_STAGE(PG8_SB(0, 1), b2 + hstep, voffB); PG8_STAGE(PG8_SA(0, 0), a2, voffA);
;             PG8_WAIT_V(8); PG8_WAIT_L(0); PG8_BAR; PG8_MMA(1, 0, At, B0); PG8_MMA(1, 1, At, B1); PG8_BAR; PG8_SCHED;
.LBB0_2452:
	ds_read_b128 v[152:155], v148
	ds_read_b128 v[156:159], v148 offset:1024
	ds_read_b128 v[160:163], v148 offset:2048
	ds_read_b128 v[164:167], v148 offset:3072
	ds_read_b128 v[168:171], v149
	ds_read_b128 v[172:175], v149 offset:1024
	ds_read_b128 v[176:179], v149 offset:2048
	ds_read_b128 v[180:183], v149 offset:3072
	s_add_i32 s76, s30, 2
	s_add_u32 s31, s28, 0xfff80080
	s_addc_u32 s34, s29, -1
	s_cmp_eq_u32 s43, s30
	s_cselect_b32 s30, s42, s52
	s_cselect_b32 s35, s3, s34
	s_cselect_b32 s34, s17, s31
	s_cselect_b32 s31, s19, s75
	v_lshl_add_u64 v[144:145], s[28:29], 0, v[138:139]
	s_add_i32 m0, s25, 0xc000
	ds_read_b128 v[184:187], v150
	ds_read_b128 v[188:191], v150 offset:1024
	ds_read_b128 v[192:195], v150 offset:2048
	ds_read_b128 v[196:199], v150 offset:3072
	ds_read_b128 v[200:203], v150 offset:4096
	ds_read_b128 v[204:207], v150 offset:5120
	ds_read_b128 v[208:211], v150 offset:6144
	ds_read_b128 v[212:215], v150 offset:7168
	global_load_lds_dwordx4 v[144:145], off
	v_lshl_add_u64 v[144:145], s[28:29], 0, v[140:141]
	s_add_i32 m0, s25, 0xe000
	s_nop 0
	global_load_lds_dwordx4 v[144:145], off
	s_waitcnt vmcnt(8)
	s_waitcnt lgkmcnt(0)
	s_setprio 1
	s_barrier
	v_mfma_f32_16x16x32_bf16 v[124:127], v[152:155], v[184:187], v[124:127]
	v_mfma_f32_16x16x32_bf16 v[116:119], v[160:163], v[184:187], v[116:119]
	v_mfma_f32_16x16x32_bf16 v[108:111], v[152:155], v[192:195], v[108:111]
	v_mfma_f32_16x16x32_bf16 v[100:103], v[160:163], v[192:195], v[100:103]
	v_mfma_f32_16x16x32_bf16 v[92:95], v[152:155], v[200:203], v[92:95]
	v_mfma_f32_16x16x32_bf16 v[84:87], v[160:163], v[200:203], v[84:87]
	v_mfma_f32_16x16x32_bf16 v[76:79], v[152:155], v[208:211], v[76:79]
	v_mfma_f32_16x16x32_bf16 v[68:71], v[160:163], v[208:211], v[68:71]
	v_mfma_f32_16x16x32_bf16 v[124:127], v[156:159], v[188:191], v[124:127]
	v_mfma_f32_16x16x32_bf16 v[116:119], v[164:167], v[188:191], v[116:119]
	v_mfma_f32_16x16x32_bf16 v[108:111], v[156:159], v[196:199], v[108:111]
	v_mfma_f32_16x16x32_bf16 v[100:103], v[164:167], v[196:199], v[100:103]
	v_mfma_f32_16x16x32_bf16 v[92:95], v[156:159], v[204:207], v[92:95]
	v_mfma_f32_16x16x32_bf16 v[84:87], v[164:167], v[204:207], v[84:87]
	v_mfma_f32_16x16x32_bf16 v[76:79], v[156:159], v[212:215], v[76:79]
	v_mfma_f32_16x16x32_bf16 v[68:71], v[164:167], v[212:215], v[68:71]
	v_mfma_f32_16x16x32_bf16 v[120:123], v[168:171], v[184:187], v[120:123]
	v_mfma_f32_16x16x32_bf16 v[112:115], v[176:179], v[184:187], v[112:115]
	v_mfma_f32_16x16x32_bf16 v[104:107], v[168:171], v[192:195], v[104:107]
	v_mfma_f32_16x16x32_bf16 v[96:99], v[176:179], v[192:195], v[96:99]
	v_mfma_f32_16x16x32_bf16 v[88:91], v[168:171], v[200:203], v[88:91]
	v_mfma_f32_16x16x32_bf16 v[80:83], v[176:179], v[200:203], v[80:83]
	v_mfma_f32_16x16x32_bf16 v[72:75], v[168:171], v[208:211], v[72:75]
	v_mfma_f32_16x16x32_bf16 v[64:67], v[176:179], v[208:211], v[64:67]
	v_mfma_f32_16x16x32_bf16 v[120:123], v[172:175], v[188:191], v[120:123]
	v_mfma_f32_16x16x32_bf16 v[112:115], v[180:183], v[188:191], v[112:115]
	v_mfma_f32_16x16x32_bf16 v[104:107], v[172:175], v[196:199], v[104:107]
	v_mfma_f32_16x16x32_bf16 v[96:99], v[180:183], v[196:199], v[96:99]
	v_mfma_f32_16x16x32_bf16 v[88:91], v[172:175], v[204:207], v[88:91]
	v_mfma_f32_16x16x32_bf16 v[80:83], v[180:183], v[204:207], v[80:83]
	v_mfma_f32_16x16x32_bf16 v[72:75], v[172:175], v[212:215], v[72:75]
	v_mfma_f32_16x16x32_bf16 v[64:67], v[180:183], v[212:215], v[64:67]
	s_barrier
	s_setprio 0
	s_add_i32 s77, s65, s38
	v_lshl_add_u64 v[144:145], s[30:31], 0, v[132:133]
	s_mov_b32 m0, s77
	ds_read_b128 v[184:187], v150 offset:16384
	ds_read_b128 v[188:191], v150 offset:17408
	ds_read_b128 v[192:195], v150 offset:18432
	ds_read_b128 v[196:199], v150 offset:19456
	ds_read_b128 v[200:203], v150 offset:20480
	ds_read_b128 v[204:207], v150 offset:21504
	ds_read_b128 v[208:211], v150 offset:22528
	ds_read_b128 v[212:215], v150 offset:23552
	global_load_lds_dwordx4 v[144:145], off
	s_add_i32 m0, s77, 0x2000
	s_add_u32 s78, s30, 0x80000
	v_lshl_add_u64 v[216:217], s[30:31], 0, v[128:129]
	s_addc_u32 s79, s31, 0
	s_add_i32 s77, s66, s38
	global_load_lds_dwordx4 v[216:217], off
	v_lshl_add_u64 v[218:219], s[78:79], 0, v[132:133]
	s_mov_b32 m0, s77
	v_lshl_add_u64 v[220:221], s[34:35], 0, v[130:131]
	global_load_lds_dwordx4 v[218:219], off
	v_lshl_add_u64 v[218:219], s[78:79], 0, v[128:129]
	s_add_i32 m0, s77, 0x2000
	s_nop 0
	global_load_lds_dwordx4 v[218:219], off
	v_lshl_add_u64 v[218:219], s[34:35], 0, v[134:135]
	s_mov_b32 m0, s25
	s_nop 0
	global_load_lds_dwordx4 v[218:219], off
	s_mov_b32 m0, s27
	s_nop 0
	global_load_lds_dwordx4 v[220:221], off
	s_waitcnt vmcnt(8)
	s_waitcnt lgkmcnt(0)
	s_setprio 1
	s_barrier
; #define PG8_STAGE(bufoff, gbase, voff) do { _Pragma("unroll") for (int _i = 0; _i < 2; ++_i) \
;         __builtin_amdgcn_global_load_lds((const unsigned*)((const char*)(gbase) + (voff)[_i]), (LAS unsigned*)(lds + (bufoff) + ldsw + _i * 8192), 16, 0, 0); } while (0)
; #define PG8_LDA(dst, b, h) do { _Pragma("unroll") for (int m = 0; m < 4; ++m) _Pragma("unroll") for (int k = 0; k < 2; ++k) dst[m][k] = *(const LAS bf16x8*)(lds + PG8_SA(b, h) + aoff + m * 2048 + k * KOFF); } while (0)
; #define PG8_LDB(dst, b, h) do { _Pragma("unroll") for (int n = 0; n < 2; ++n) _Pragma("unroll") for (int k = 0; k < 2; ++k) dst[n][k] = *(const LAS bf16x8*)(lds + PG8_SB(b, h) + boff + n * 2048 + k * KOFF); } while (0)
; #define PG8_WAIT_V(n) asm volatile("s_waitcnt vmcnt(" #n ")" ::: "memory")
; #define PG8_WAIT_L(n) asm volatile("s_waitcnt lgkmcnt(" #n ")" ::: "memory")
; #define PG8_BAR __builtin_amdgcn_s_barrier()
; #define PG8_SCHED __builtin_amdgcn_sched_barrier(0)
; template <class Epi, bool ALIGN_EPI = true, bool FP8 = false>
; __device__ __forceinline__ void gemm_phase(LAS unsigned char* lds, const Gemm g, const StaticOrder& S, const Epi& E, const int wid) {
;     ...
;             PG8_WAIT_V(8); PG8_WAIT_L(0); PG8_BAR; PG8_MMA(1, 0, At, B0); PG8_MMA(1, 1, At, B1); PG8_BAR; PG8_SCHED;
;             PG8_LDB(B0, 1, 0); PG8_LDB(B1, 1, 1); PG8_SCHED; PG8_LDA(At, 1, 0); PG8_STAGE(PG8_SA(0, 1), a2 + hstep, voffA);
;             PG8_WAIT_V(8); PG8_WAIT_L(0); PG8_BAR; PG8_MMA(0, 0, At, B0); PG8_MMA(0, 1, At, B1); PG8_BAR; PG8_SCHED;
	v_mfma_f32_16x16x32_bf16 v[60:63], v[152:155], v[184:187], v[60:63]
	v_mfma_f32_16x16x32_bf16 v[52:55], v[160:163], v[184:187], v[52:55]
	v_mfma_f32_16x16x32_bf16 v[44:47], v[152:155], v[192:195], v[44:47]
	v_mfma_f32_16x16x32_bf16 v[36:39], v[160:163], v[192:195], v[36:39]
	v_mfma_f32_16x16x32_bf16 v[28:31], v[152:155], v[200:203], v[28:31]
	v_mfma_f32_16x16x32_bf16 v[20:23], v[160:163], v[200:203], v[20:23]
	v_mfma_f32_16x16x32_bf16 v[12:15], v[152:155], v[208:211], v[12:15]
	v_mfma_f32_16x16x32_bf16 v[4:7], v[160:163], v[208:211], v[4:7]
	v_mfma_f32_16x16x32_bf16 v[60:63], v[156:159], v[188:191], v[60:63]
	v_mfma_f32_16x16x32_bf16 v[52:55], v[164:167], v[188:191], v[52:55]
	v_mfma_f32_16x16x32_bf16 v[44:47], v[156:159], v[196:199], v[44:47]
	v_mfma_f32_16x16x32_bf16 v[36:39], v[164:167], v[196:199], v[36:39]
	v_mfma_f32_16x16x32_bf16 v[28:31], v[156:159], v[204:207], v[28:31]
	v_mfma_f32_16x16x32_bf16 v[20:23], v[164:167], v[204:207], v[20:23]
	v_mfma_f32_16x16x32_bf16 v[12:15], v[156:159], v[212:215], v[12:15]
	v_mfma_f32_16x16x32_bf16 v[4:7], v[164:167], v[212:215], v[4:7]
	v_mfma_f32_16x16x32_bf16 v[56:59], v[168:171], v[184:187], v[56:59]
	v_mfma_f32_16x16x32_bf16 v[48:51], v[176:179], v[184:187], v[48:51]
	v_mfma_f32_16x16x32_bf16 v[40:43], v[168:171], v[192:195], v[40:43]
	v_mfma_f32_16x16x32_bf16 v[32:35], v[176:179], v[192:195], v[32:35]
	v_mfma_f32_16x16x32_bf16 v[24:27], v[168:171], v[200:203], v[24:27]
	v_mfma_f32_16x16x32_bf16 v[16:19], v[176:179], v[200:203], v[16:19]
	v_mfma_f32_16x16x32_bf16 v[8:11], v[168:171], v[208:211], v[8:11]
	v_mfma_f32_16x16x32_bf16 v[0:3], v[176:179], v[208:211], v[0:3]
	v_mfma_f32_16x16x32_bf16 v[56:59], v[172:175], v[188:191], v[56:59]
	v_mfma_f32_16x16x32_bf16 v[48:51], v[180:183], v[188:191], v[48:51]
	v_mfma_f32_16x16x32_bf16 v[40:43], v[172:175], v[196:199], v[40:43]
	v_mfma_f32_16x16x32_bf16 v[32:35], v[180:183], v[196:199], v[32:35]
	v_mfma_f32_16x16x32_bf16 v[24:27], v[172:175], v[204:207], v[24:27]
	v_mfma_f32_16x16x32_bf16 v[16:19], v[180:183], v[204:207], v[16:19]
	v_mfma_f32_16x16x32_bf16 v[8:11], v[172:175], v[212:215], v[8:11]
	v_mfma_f32_16x16x32_bf16 v[0:3], v[180:183], v[212:215], v[0:3]
	s_barrier
	s_setprio 0
	s_add_i32 s77, 0, 0x18000
	s_add_i32 s78, 0, 0x1c000
	v_add_u32_e32 v164, s77, v147
	v_add_u32_e32 v180, s78, v147
	ds_read_b128 v[152:155], v164
	ds_read_b128 v[156:159], v164 offset:1024
	ds_read_b128 v[160:163], v164 offset:2048
	ds_read_b128 v[164:167], v164 offset:3072
	ds_read_b128 v[168:171], v180
	ds_read_b128 v[172:175], v180 offset:1024
	ds_read_b128 v[176:179], v180 offset:2048
	ds_read_b128 v[180:183], v180 offset:3072
	s_add_u32 s34, s34, 0x80000
	s_addc_u32 s35, s35, 0
	s_mov_b32 m0, s39
	v_lshl_add_u64 v[222:223], s[34:35], 0, v[134:135]
	ds_read_b128 v[184:187], v150 offset:32768
	ds_read_b128 v[188:191], v150 offset:33792
	ds_read_b128 v[192:195], v150 offset:34816
	ds_read_b128 v[196:199], v150 offset:35840
	ds_read_b128 v[200:203], v150 offset:36864
	ds_read_b128 v[204:207], v150 offset:37888
	ds_read_b128 v[208:211], v150 offset:38912
	ds_read_b128 v[212:215], v150 offset:39936
	global_load_lds_dwordx4 v[222:223], off
	v_lshl_add_u64 v[222:223], s[34:35], 0, v[130:131]
	s_mov_b32 m0, s48
	s_nop 0
	global_load_lds_dwordx4 v[222:223], off
	s_waitcnt vmcnt(8)
	s_waitcnt lgkmcnt(0)
	s_setprio 1
	s_barrier
	v_mfma_f32_16x16x32_bf16 v[124:127], v[152:155], v[184:187], v[124:127]
	v_mfma_f32_16x16x32_bf16 v[116:119], v[160:163], v[184:187], v[116:119]
	v_mfma_f32_16x16x32_bf16 v[108:111], v[152:155], v[192:195], v[108:111]
	v_mfma_f32_16x16x32_bf16 v[100:103], v[160:163], v[192:195], v[100:103]
	v_mfma_f32_16x16x32_bf16 v[92:95], v[152:155], v[200:203], v[92:95]
	v_mfma_f32_16x16x32_bf16 v[84:87], v[160:163], v[200:203], v[84:87]
	v_mfma_f32_16x16x32_bf16 v[76:79], v[152:155], v[208:211], v[76:79]
	v_mfma_f32_16x16x32_bf16 v[68:71], v[160:163], v[208:211], v[68:71]
	v_mfma_f32_16x16x32_bf16 v[124:127], v[156:159], v[188:191], v[124:127]
	v_mfma_f32_16x16x32_bf16 v[116:119], v[164:167], v[188:191], v[116:119]
	v_mfma_f32_16x16x32_bf16 v[108:111], v[156:159], v[196:199], v[108:111]
	v_mfma_f32_16x16x32_bf16 v[100:103], v[164:167], v[196:199], v[100:103]
	v_mfma_f32_16x16x32_bf16 v[92:95], v[156:159], v[204:207], v[92:95]
	v_mfma_f32_16x16x32_bf16 v[84:87], v[164:167], v[204:207], v[84:87]
	v_mfma_f32_16x16x32_bf16 v[76:79], v[156:159], v[212:215], v[76:79]
	v_mfma_f32_16x16x32_bf16 v[68:71], v[164:167], v[212:215], v[68:71]
	v_mfma_f32_16x16x32_bf16 v[120:123], v[168:171], v[184:187], v[120:123]
	v_mfma_f32_16x16x32_bf16 v[112:115], v[176:179], v[184:187], v[112:115]
	v_mfma_f32_16x16x32_bf16 v[104:107], v[168:171], v[192:195], v[104:107]
	v_mfma_f32_16x16x32_bf16 v[96:99], v[176:179], v[192:195], v[96:99]
	v_mfma_f32_16x16x32_bf16 v[88:91], v[168:171], v[200:203], v[88:91]
	v_mfma_f32_16x16x32_bf16 v[80:83], v[176:179], v[200:203], v[80:83]
	v_mfma_f32_16x16x32_bf16 v[72:75], v[168:171], v[208:211], v[72:75]
	v_mfma_f32_16x16x32_bf16 v[64:67], v[176:179], v[208:211], v[64:67]
	v_mfma_f32_16x16x32_bf16 v[120:123], v[172:175], v[188:191], v[120:123]
	v_mfma_f32_16x16x32_bf16 v[112:115], v[180:183], v[188:191], v[112:115]
	v_mfma_f32_16x16x32_bf16 v[104:107], v[172:175], v[196:199], v[104:107]
	v_mfma_f32_16x16x32_bf16 v[96:99], v[180:183], v[196:199], v[96:99]
	v_mfma_f32_16x16x32_bf16 v[88:91], v[172:175], v[204:207], v[88:91]
	v_mfma_f32_16x16x32_bf16 v[80:83], v[180:183], v[204:207], v[80:83]
	v_mfma_f32_16x16x32_bf16 v[72:75], v[172:175], v[212:215], v[72:75]
	v_mfma_f32_16x16x32_bf16 v[64:67], v[180:183], v[212:215], v[64:67]
	s_barrier
; #define PG8_STAGE(bufoff, gbase, voff) do { _Pragma("unroll") for (int _i = 0; _i < 2; ++_i) \
;         __builtin_amdgcn_global_load_lds((const unsigned*)((const char*)(gbase) + (voff)[_i]), (LAS unsigned*)(lds + (bufoff) + ldsw + _i * 8192), 16, 0, 0); } while (0)
; #define PG8_LDA(dst, b, h) do { _Pragma("unroll") for (int m = 0; m < 4; ++m) _Pragma("unroll") for (int k = 0; k < 2; ++k) dst[m][k] = *(const LAS bf16x8*)(lds + PG8_SA(b, h) + aoff + m * 2048 + k * KOFF); } while (0)
; #define PG8_WAIT_V(n) asm volatile("s_waitcnt vmcnt(" #n ")" ::: "memory")
; #define PG8_WAIT_L(n) asm volatile("s_waitcnt lgkmcnt(" #n ")" ::: "memory")
; #define PG8_BAR __builtin_amdgcn_s_barrier()
; #define PG8_SCHED __builtin_amdgcn_sched_barrier(0)
; template <class Epi, bool ALIGN_EPI = true, bool FP8 = false>
; __device__ __forceinline__ void gemm_phase(LAS unsigned char* lds, const Gemm g, const StaticOrder& S, const Epi& E, const int wid) {
;     ...
;             PG8_LDA(At, 1, 1); PG8_STAGE(PG8_SB(1, 0), b3, voffB); PG8_STAGE(PG8_SB(1, 1), b3 + hstep, voffB); PG8_STAGE(PG8_SA(1, 0), a3, voffA);
;             PG8_WAIT_V(8); PG8_WAIT_L(0); PG8_BAR; PG8_MMA(1, 0, At, B0); PG8_MMA(1, 1, At, B1); PG8_BAR; PG8_SCHED;
;         }
;         if constexpr (ALIGN_EPI) { if (wr == 0) PG8_BAR; }
	s_setprio 0
	s_add_i32 s34, s77, s38
	v_lshl_add_u64 v[144:145], v[144:145], 0, s[14:15]
	s_mov_b32 m0, s34
	ds_read_b128 v[184:187], v150 offset:49152
	ds_read_b128 v[188:191], v150 offset:50176
	ds_read_b128 v[192:195], v150 offset:51200
	ds_read_b128 v[196:199], v150 offset:52224
	ds_read_b128 v[200:203], v150 offset:53248
	ds_read_b128 v[204:207], v150 offset:54272
	ds_read_b128 v[208:211], v150 offset:55296
	ds_read_b128 v[212:215], v150 offset:56320
	global_load_lds_dwordx4 v[144:145], off
	s_add_i32 m0, s34, 0x2000
	s_add_u32 s30, s30, 0x80080
	v_lshl_add_u64 v[144:145], v[216:217], 0, s[14:15]
	s_addc_u32 s31, s31, 0
	s_add_i32 s34, s78, s38
	global_load_lds_dwordx4 v[144:145], off
	v_lshl_add_u64 v[144:145], s[30:31], 0, v[132:133]
	s_mov_b32 m0, s34
	s_nop 0
	global_load_lds_dwordx4 v[144:145], off
	v_lshl_add_u64 v[144:145], s[30:31], 0, v[128:129]
	s_add_i32 m0, s34, 0x2000
	s_nop 0
	global_load_lds_dwordx4 v[144:145], off
	v_lshl_add_u64 v[144:145], v[218:219], 0, s[14:15]
	s_mov_b32 m0, s53
	s_nop 0
	global_load_lds_dwordx4 v[144:145], off
	v_lshl_add_u64 v[144:145], v[220:221], 0, s[14:15]
	s_mov_b32 m0, s55
	s_nop 0
	global_load_lds_dwordx4 v[144:145], off
	s_waitcnt vmcnt(8)
	s_waitcnt lgkmcnt(0)
	s_setprio 1
	s_barrier
	v_mfma_f32_16x16x32_bf16 v[60:63], v[152:155], v[184:187], v[60:63]
	v_mfma_f32_16x16x32_bf16 v[52:55], v[160:163], v[184:187], v[52:55]
	v_mfma_f32_16x16x32_bf16 v[44:47], v[152:155], v[192:195], v[44:47]
	v_mfma_f32_16x16x32_bf16 v[36:39], v[160:163], v[192:195], v[36:39]
	v_mfma_f32_16x16x32_bf16 v[28:31], v[152:155], v[200:203], v[28:31]
	v_mfma_f32_16x16x32_bf16 v[20:23], v[160:163], v[200:203], v[20:23]
	v_mfma_f32_16x16x32_bf16 v[12:15], v[152:155], v[208:211], v[12:15]
	v_mfma_f32_16x16x32_bf16 v[4:7], v[160:163], v[208:211], v[4:7]
	v_mfma_f32_16x16x32_bf16 v[60:63], v[156:159], v[188:191], v[60:63]
	v_mfma_f32_16x16x32_bf16 v[52:55], v[164:167], v[188:191], v[52:55]
	v_mfma_f32_16x16x32_bf16 v[44:47], v[156:159], v[196:199], v[44:47]
	v_mfma_f32_16x16x32_bf16 v[36:39], v[164:167], v[196:199], v[36:39]
	v_mfma_f32_16x16x32_bf16 v[28:31], v[156:159], v[204:207], v[28:31]
	v_mfma_f32_16x16x32_bf16 v[20:23], v[164:167], v[204:207], v[20:23]
	v_mfma_f32_16x16x32_bf16 v[12:15], v[156:159], v[212:215], v[12:15]
	v_mfma_f32_16x16x32_bf16 v[4:7], v[164:167], v[212:215], v[4:7]
	v_mfma_f32_16x16x32_bf16 v[56:59], v[168:171], v[184:187], v[56:59]
	v_mfma_f32_16x16x32_bf16 v[48:51], v[176:179], v[184:187], v[48:51]
	v_mfma_f32_16x16x32_bf16 v[40:43], v[168:171], v[192:195], v[40:43]
	v_mfma_f32_16x16x32_bf16 v[32:35], v[176:179], v[192:195], v[32:35]
	v_mfma_f32_16x16x32_bf16 v[24:27], v[168:171], v[200:203], v[24:27]
	v_mfma_f32_16x16x32_bf16 v[16:19], v[176:179], v[200:203], v[16:19]
	v_mfma_f32_16x16x32_bf16 v[8:11], v[168:171], v[208:211], v[8:11]
	v_mfma_f32_16x16x32_bf16 v[0:3], v[176:179], v[208:211], v[0:3]
	v_mfma_f32_16x16x32_bf16 v[56:59], v[172:175], v[188:191], v[56:59]
	v_mfma_f32_16x16x32_bf16 v[48:51], v[180:183], v[188:191], v[48:51]
	v_mfma_f32_16x16x32_bf16 v[40:43], v[172:175], v[196:199], v[40:43]
	v_mfma_f32_16x16x32_bf16 v[32:35], v[180:183], v[196:199], v[32:35]
	v_mfma_f32_16x16x32_bf16 v[24:27], v[172:175], v[204:207], v[24:27]
	v_mfma_f32_16x16x32_bf16 v[16:19], v[180:183], v[204:207], v[16:19]
	v_mfma_f32_16x16x32_bf16 v[8:11], v[172:175], v[212:215], v[8:11]
	v_mfma_f32_16x16x32_bf16 v[0:3], v[180:183], v[212:215], v[0:3]
	s_barrier
	s_setprio 0
	s_add_u32 s28, s28, 0x100
	s_addc_u32 s29, s29, 0
	s_add_u32 s52, s52, 0x100
	s_addc_u32 s75, s75, 0
	s_cmp_ge_u32 s76, s54
	s_mov_b32 s30, s76
	s_cbranch_scc0 .LBB0_2452
	s_and_b64 vcc, exec, s[12:13]
	s_cbranch_vccz .LBB0_2455

; #define PG8_STAGE(bufoff, gbase, voff) do { _Pragma("unroll") for (int _i = 0; _i < 2; ++_i) \
;         __builtin_amdgcn_global_load_lds((const unsigned*)((const char*)(gbase) + (voff)[_i]), (LAS unsigned*)(lds + (bufoff) + ldsw + _i * 8192), 16, 0, 0); } while (0)
; #define PG8_LDA(dst, b, h) do { _Pragma("unroll") for (int m = 0; m < 4; ++m) _Pragma("unroll") for (int k = 0; k < 2; ++k) dst[m][k] = *(const LAS bf16x8*)(lds + PG8_SA(b, h) + aoff + m * 2048 + k * KOFF); } while (0)
; #define PG8_LDB(dst, b, h) do { _Pragma("unroll") for (int n = 0; n < 2; ++n) _Pragma("unroll") for (int k = 0; k < 2; ++k) dst[n][k] = *(const LAS bf16x8*)(lds + PG8_SB(b, h) + boff + n * 2048 + k * KOFF); } while (0)
; #define PG8_WAIT_V(n) asm volatile("s_waitcnt vmcnt(" #n ")" ::: "memory")
; #define PG8_WAIT_L(n) asm volatile("s_waitcnt lgkmcnt(" #n ")" ::: "memory")
; #define PG8_BAR __builtin_amdgcn_s_barrier()
; #define PG8_SCHED __builtin_amdgcn_sched_barrier(0)
; template <class Epi, bool ALIGN_EPI = true, bool FP8 = false>
; __device__ __forceinline__ void gemm_phase(LAS unsigned char* lds, const Gemm g, const StaticOrder& S, const Epi& E, const int wid) {
;     ...
;             const char* a1 = cA + (size_t)(t + 1) * kstep;
;             const char* a2 = last ? nA : cA + (size_t)(t + 2) * kstep; const char* b2 = last ? nB : cB + (size_t)(t + 2) * kstep;
;             const char* a3 = a2 + kstep; const char* b3 = b2 + kstep;
;             PG8_LDB(B0, 0, 0); PG8_LDB(B1, 0, 1); PG8_SCHED; PG8_LDA(At, 0, 0); PG8_STAGE(PG8_SA(1, 1), a1 + hstep, voffA);
;             PG8_WAIT_V(8); PG8_WAIT_L(0); PG8_BAR; PG8_MMA(0, 0, At, B0); PG8_MMA(0, 1, At, B1); PG8_BAR; PG8_SCHED;
;             PG8_LDA(At, 0, 1); PG8_STAGE(PG8_SB(0, 0), b2, voffB); PG8_STAGE(PG8_SB(0, 1), b2 + hstep, voffB); PG8_STAGE(PG8_SA(0, 0), a2, voffA);
;             PG8_WAIT_V(8); PG8_WAIT_L(0); PG8_BAR; PG8_MMA(1, 0, At, B0); PG8_MMA(1, 1, At, B1); PG8_BAR; PG8_SCHED;
.LBB0_2536:
	ds_read_b128 v[152:155], v188
	ds_read_b128 v[156:159], v188 offset:1024
	ds_read_b128 v[144:147], v188 offset:2048
	ds_read_b128 v[148:151], v188 offset:3072
	ds_read_b128 v[136:139], v189
	ds_read_b128 v[140:143], v189 offset:1024
	ds_read_b128 v[128:131], v189 offset:2048
	ds_read_b128 v[132:135], v189 offset:3072
	s_add_i32 s42, s26, 2
	s_add_u32 s27, s24, 0xfff50080
	s_addc_u32 s28, s25, -1
	s_cmp_eq_u32 s81, s26
	s_cselect_b32 s26, s20, s82
	s_cselect_b32 s29, s7, s28
	s_cselect_b32 s28, s6, s27
	s_cselect_b32 s27, s21, s83
	v_lshl_add_u64 v[216:217], s[24:25], 0, v[172:173]
	s_add_i32 m0, s34, 0xc000
	ds_read_b128 v[178:181], v190
	ds_read_b128 v[182:185], v190 offset:1024
	ds_read_b128 v[192:195], v190 offset:2048
	ds_read_b128 v[196:199], v190 offset:3072
	ds_read_b128 v[200:203], v190 offset:4096
	ds_read_b128 v[204:207], v190 offset:5120
	ds_read_b128 v[208:211], v190 offset:6144
	ds_read_b128 v[212:215], v190 offset:7168
	global_load_lds_dwordx4 v[216:217], off
	v_lshl_add_u64 v[216:217], s[24:25], 0, v[174:175]
	s_add_i32 m0, s34, 0xe000
	s_nop 0
	global_load_lds_dwordx4 v[216:217], off
	s_waitcnt vmcnt(8)
	s_waitcnt lgkmcnt(0)
	s_setprio 1
	s_barrier
	v_mfma_f32_16x16x128_f8f6f4 v[120:123], v[152:159], v[178:185], v[120:123]
	v_mfma_f32_16x16x128_f8f6f4 v[124:127], v[144:151], v[178:185], v[124:127]
	v_mfma_f32_16x16x128_f8f6f4 v[112:115], v[152:159], v[192:199], v[112:115]
	v_mfma_f32_16x16x128_f8f6f4 v[116:119], v[144:151], v[192:199], v[116:119]
	v_mfma_f32_16x16x128_f8f6f4 v[96:99], v[152:159], v[200:207], v[96:99]
	v_mfma_f32_16x16x128_f8f6f4 v[100:103], v[144:151], v[200:207], v[100:103]
	v_mfma_f32_16x16x128_f8f6f4 v[80:83], v[152:159], v[208:215], v[80:83]
	v_mfma_f32_16x16x128_f8f6f4 v[84:87], v[144:151], v[208:215], v[84:87]
	v_mfma_f32_16x16x128_f8f6f4 v[104:107], v[136:143], v[178:185], v[104:107]
	v_mfma_f32_16x16x128_f8f6f4 v[108:111], v[128:135], v[178:185], v[108:111]
	v_mfma_f32_16x16x128_f8f6f4 v[88:91], v[136:143], v[192:199], v[88:91]
	v_mfma_f32_16x16x128_f8f6f4 v[92:95], v[128:135], v[192:199], v[92:95]
	v_mfma_f32_16x16x128_f8f6f4 v[72:75], v[136:143], v[200:207], v[72:75]
	v_mfma_f32_16x16x128_f8f6f4 v[76:79], v[128:135], v[200:207], v[76:79]
	v_mfma_f32_16x16x128_f8f6f4 v[64:67], v[136:143], v[208:215], v[64:67]
	v_mfma_f32_16x16x128_f8f6f4 v[68:71], v[128:135], v[208:215], v[68:71]
	s_barrier
	s_setprio 0
	s_add_i32 s43, s64, s31
	v_lshl_add_u64 v[178:179], s[26:27], 0, v[162:163]
	s_mov_b32 m0, s43
	ds_read_b128 v[192:195], v190 offset:16384
	ds_read_b128 v[196:199], v190 offset:17408
	ds_read_b128 v[200:203], v190 offset:18432
	ds_read_b128 v[204:207], v190 offset:19456
	ds_read_b128 v[208:211], v190 offset:20480
	ds_read_b128 v[212:215], v190 offset:21504
	ds_read_b128 v[216:219], v190 offset:22528
	ds_read_b128 v[220:223], v190 offset:23552
	global_load_lds_dwordx4 v[178:179], off
	s_add_i32 m0, s43, 0x2000
	s_add_u32 s84, s26, 0xb0000
	v_lshl_add_u64 v[180:181], s[26:27], 0, v[166:167]
	s_addc_u32 s85, s27, 0
	s_add_i32 s43, s65, s31
	global_load_lds_dwordx4 v[180:181], off
	v_lshl_add_u64 v[182:183], s[84:85], 0, v[162:163]
	s_mov_b32 m0, s43
	v_lshl_add_u64 v[184:185], s[28:29], 0, v[164:165]
	global_load_lds_dwordx4 v[182:183], off
	v_lshl_add_u64 v[182:183], s[84:85], 0, v[166:167]
	s_add_i32 m0, s43, 0x2000
	s_nop 0
	global_load_lds_dwordx4 v[182:183], off
	v_lshl_add_u64 v[182:183], s[28:29], 0, v[160:161]
	s_mov_b32 m0, s34
	s_nop 0
	global_load_lds_dwordx4 v[182:183], off
	s_mov_b32 m0, s35
	s_nop 0
	global_load_lds_dwordx4 v[184:185], off
	s_waitcnt vmcnt(8)
	s_waitcnt lgkmcnt(0)
	s_setprio 1
	s_barrier
	v_mfma_f32_16x16x128_f8f6f4 v[56:59], v[152:159], v[192:199], v[56:59]
	v_mfma_f32_16x16x128_f8f6f4 v[60:63], v[144:151], v[192:199], v[60:63]
	v_mfma_f32_16x16x128_f8f6f4 v[48:51], v[152:159], v[200:207], v[48:51]
	v_mfma_f32_16x16x128_f8f6f4 v[52:55], v[144:151], v[200:207], v[52:55]
	v_mfma_f32_16x16x128_f8f6f4 v[32:35], v[152:159], v[208:215], v[32:35]
	v_mfma_f32_16x16x128_f8f6f4 v[224:227], v[144:151], v[208:215], v[36:39]
	v_mfma_f32_16x16x128_f8f6f4 v[228:231], v[152:159], v[216:223], v[16:19]
	v_mfma_f32_16x16x128_f8f6f4 v[232:235], v[144:151], v[216:223], v[20:23]
	v_mfma_f32_16x16x128_f8f6f4 v[44:47], v[128:135], v[192:199], v[44:47]
	v_mfma_f32_16x16x128_f8f6f4 v[236:239], v[136:143], v[192:199], v[40:43]
	v_mfma_f32_16x16x128_f8f6f4 v[240:243], v[136:143], v[200:207], v[24:27]
	v_mfma_f32_16x16x128_f8f6f4 v[200:203], v[128:135], v[200:207], v[28:31]
	v_mfma_f32_16x16x128_f8f6f4 v[204:207], v[136:143], v[208:215], v[8:11]
	v_mfma_f32_16x16x128_f8f6f4 v[208:211], v[128:135], v[208:215], v[12:15]
	v_mfma_f32_16x16x128_f8f6f4 v[212:215], v[136:143], v[216:223], v[0:3]
	v_mfma_f32_16x16x128_f8f6f4 v[216:219], v[128:135], v[216:223], v[4:7]
	s_barrier
; #define PG8_STAGE(bufoff, gbase, voff) do { _Pragma("unroll") for (int _i = 0; _i < 2; ++_i) \
;         __builtin_amdgcn_global_load_lds((const unsigned*)((const char*)(gbase) + (voff)[_i]), (LAS unsigned*)(lds + (bufoff) + ldsw + _i * 8192), 16, 0, 0); } while (0)
; #define PG8_LDA(dst, b, h) do { _Pragma("unroll") for (int m = 0; m < 4; ++m) _Pragma("unroll") for (int k = 0; k < 2; ++k) dst[m][k] = *(const LAS bf16x8*)(lds + PG8_SA(b, h) + aoff + m * 2048 + k * KOFF); } while (0)
; #define PG8_LDB(dst, b, h) do { _Pragma("unroll") for (int n = 0; n < 2; ++n) _Pragma("unroll") for (int k = 0; k < 2; ++k) dst[n][k] = *(const LAS bf16x8*)(lds + PG8_SB(b, h) + boff + n * 2048 + k * KOFF); } while (0)
; #define PG8_WAIT_V(n) asm volatile("s_waitcnt vmcnt(" #n ")" ::: "memory")
; #define PG8_WAIT_L(n) asm volatile("s_waitcnt lgkmcnt(" #n ")" ::: "memory")
; #define PG8_BAR __builtin_amdgcn_s_barrier()
; #define PG8_SCHED __builtin_amdgcn_sched_barrier(0)
; template <class Epi, bool ALIGN_EPI = true, bool FP8 = false>
; __device__ __forceinline__ void gemm_phase(LAS unsigned char* lds, const Gemm g, const StaticOrder& S, const Epi& E, const int wid) {
;     ...
;             PG8_LDB(B0, 1, 0); PG8_LDB(B1, 1, 1); PG8_SCHED; PG8_LDA(At, 1, 0); PG8_STAGE(PG8_SA(0, 1), a2 + hstep, voffA);
;             PG8_WAIT_V(8); PG8_WAIT_L(0); PG8_BAR; PG8_MMA(0, 0, At, B0); PG8_MMA(0, 1, At, B1); PG8_BAR; PG8_SCHED;
;             PG8_LDA(At, 1, 1); PG8_STAGE(PG8_SB(1, 0), b3, voffB); PG8_STAGE(PG8_SB(1, 1), b3 + hstep, voffB); PG8_STAGE(PG8_SA(1, 0), a3, voffA);
;             PG8_WAIT_V(8); PG8_WAIT_L(0); PG8_BAR; PG8_MMA(1, 0, At, B0); PG8_MMA(1, 1, At, B1); PG8_BAR; PG8_SCHED;
;         }
;         if constexpr (ALIGN_EPI) { if (wr == 0) PG8_BAR; }
	s_setprio 0
	s_add_i32 s43, 0, 0x18000
	s_add_i32 s54, 0, 0x1c000
	s_nop 0
	v_add_u32_e32 v12, s43, v187
	v_add_u32_e32 v16, s54, v187
	ds_read_b128 v[0:3], v12
	ds_read_b128 v[4:7], v12 offset:1024
	ds_read_b128 v[8:11], v12 offset:2048
	ds_read_b128 v[12:15], v12 offset:3072
	ds_read_b128 v[128:131], v16
	ds_read_b128 v[132:135], v16 offset:1024
	ds_read_b128 v[136:139], v16 offset:2048
	ds_read_b128 v[140:143], v16 offset:3072
	s_add_u32 s28, s28, 0xb0000
	s_addc_u32 s29, s29, 0
	s_mov_b32 m0, s36
	v_lshl_add_u64 v[152:153], s[28:29], 0, v[160:161]
	ds_read_b128 v[16:19], v190 offset:32768
	ds_read_b128 v[20:23], v190 offset:33792
	ds_read_b128 v[24:27], v190 offset:34816
	ds_read_b128 v[28:31], v190 offset:35840
	ds_read_b128 v[36:39], v190 offset:36864
	ds_read_b128 v[40:43], v190 offset:37888
	ds_read_b128 v[144:147], v190 offset:38912
	ds_read_b128 v[148:151], v190 offset:39936
	global_load_lds_dwordx4 v[152:153], off
	v_lshl_add_u64 v[152:153], s[28:29], 0, v[164:165]
	s_mov_b32 m0, s37
	s_nop 0
	global_load_lds_dwordx4 v[152:153], off
	s_waitcnt vmcnt(8)
	s_waitcnt lgkmcnt(0)
	s_setprio 1
	s_barrier
	v_mfma_f32_16x16x128_f8f6f4 v[120:123], v[0:7], v[16:23], v[120:123]
	v_mfma_f32_16x16x128_f8f6f4 v[124:127], v[8:15], v[16:23], v[124:127]
	v_mfma_f32_16x16x128_f8f6f4 v[112:115], v[0:7], v[24:31], v[112:115]
	v_mfma_f32_16x16x128_f8f6f4 v[116:119], v[8:15], v[24:31], v[116:119]
	v_mfma_f32_16x16x128_f8f6f4 v[96:99], v[0:7], v[36:43], v[96:99]
	v_mfma_f32_16x16x128_f8f6f4 v[100:103], v[8:15], v[36:43], v[100:103]
	v_mfma_f32_16x16x128_f8f6f4 v[80:83], v[0:7], v[144:151], v[80:83]
	v_mfma_f32_16x16x128_f8f6f4 v[84:87], v[8:15], v[144:151], v[84:87]
	v_mfma_f32_16x16x128_f8f6f4 v[104:107], v[128:135], v[16:23], v[104:107]
	v_mfma_f32_16x16x128_f8f6f4 v[108:111], v[136:143], v[16:23], v[108:111]
	v_mfma_f32_16x16x128_f8f6f4 v[88:91], v[128:135], v[24:31], v[88:91]
	v_mfma_f32_16x16x128_f8f6f4 v[92:95], v[136:143], v[24:31], v[92:95]
	v_mfma_f32_16x16x128_f8f6f4 v[72:75], v[128:135], v[36:43], v[72:75]
	v_mfma_f32_16x16x128_f8f6f4 v[76:79], v[136:143], v[36:43], v[76:79]
	v_mfma_f32_16x16x128_f8f6f4 v[64:67], v[128:135], v[144:151], v[64:67]
	v_mfma_f32_16x16x128_f8f6f4 v[68:71], v[136:143], v[144:151], v[68:71]
	s_barrier
	s_setprio 0
	s_add_i32 s28, s43, s31
	v_lshl_add_u64 v[16:17], v[178:179], 0, s[14:15]
	s_mov_b32 m0, s28
	ds_read_b128 v[24:27], v190 offset:49152
	ds_read_b128 v[28:31], v190 offset:50176
	ds_read_b128 v[144:147], v190 offset:51200
	ds_read_b128 v[148:151], v190 offset:52224
	ds_read_b128 v[152:155], v190 offset:53248
	ds_read_b128 v[156:159], v190 offset:54272
	ds_read_b128 v[192:195], v190 offset:55296
	ds_read_b128 v[196:199], v190 offset:56320
	global_load_lds_dwordx4 v[16:17], off
	s_add_i32 m0, s28, 0x2000
	s_add_u32 s26, s26, 0xb0080
	v_lshl_add_u64 v[16:17], v[180:181], 0, s[14:15]
	s_addc_u32 s27, s27, 0
	s_add_i32 s28, s54, s31
	global_load_lds_dwordx4 v[16:17], off
	v_lshl_add_u64 v[16:17], s[26:27], 0, v[162:163]
	s_mov_b32 m0, s28
	s_nop 0
	global_load_lds_dwordx4 v[16:17], off
	v_lshl_add_u64 v[16:17], s[26:27], 0, v[166:167]
	s_add_i32 m0, s28, 0x2000
	s_nop 0
	global_load_lds_dwordx4 v[16:17], off
	v_lshl_add_u64 v[16:17], v[182:183], 0, s[14:15]
	s_mov_b32 m0, s52
	s_nop 0
	global_load_lds_dwordx4 v[16:17], off
	v_lshl_add_u64 v[16:17], v[184:185], 0, s[14:15]
	s_mov_b32 m0, s53
	s_nop 0
	global_load_lds_dwordx4 v[16:17], off
	s_waitcnt vmcnt(8)
	s_waitcnt lgkmcnt(0)
	s_setprio 1
	s_barrier
	v_mfma_f32_16x16x128_f8f6f4 v[56:59], v[0:7], v[24:31], v[56:59]
	v_mfma_f32_16x16x128_f8f6f4 v[60:63], v[8:15], v[24:31], v[60:63]
	v_mfma_f32_16x16x128_f8f6f4 v[48:51], v[0:7], v[144:151], v[48:51]
	v_mfma_f32_16x16x128_f8f6f4 v[52:55], v[8:15], v[144:151], v[52:55]
	v_mfma_f32_16x16x128_f8f6f4 v[32:35], v[0:7], v[152:159], v[32:35]
	v_mfma_f32_16x16x128_f8f6f4 v[36:39], v[8:15], v[152:159], v[224:227]
	v_mfma_f32_16x16x128_f8f6f4 v[16:19], v[0:7], v[192:199], v[228:231]
	v_mfma_f32_16x16x128_f8f6f4 v[20:23], v[8:15], v[192:199], v[232:235]
	v_mfma_f32_16x16x128_f8f6f4 v[40:43], v[128:135], v[24:31], v[236:239]
	v_mfma_f32_16x16x128_f8f6f4 v[44:47], v[136:143], v[24:31], v[44:47]
	v_mfma_f32_16x16x128_f8f6f4 v[24:27], v[128:135], v[144:151], v[240:243]
	v_mfma_f32_16x16x128_f8f6f4 v[28:31], v[136:143], v[144:151], v[200:203]
	v_mfma_f32_16x16x128_f8f6f4 v[8:11], v[128:135], v[152:159], v[204:207]
	v_mfma_f32_16x16x128_f8f6f4 v[12:15], v[136:143], v[152:159], v[208:211]
	v_mfma_f32_16x16x128_f8f6f4 v[0:3], v[128:135], v[192:199], v[212:215]
	v_mfma_f32_16x16x128_f8f6f4 v[4:7], v[136:143], v[192:199], v[216:219]
	s_barrier
	s_setprio 0
	s_add_u32 s24, s24, 0x100
	s_addc_u32 s25, s25, 0
	s_add_u32 s82, s82, 0x100
	s_addc_u32 s83, s83, 0
	s_cmp_ge_u32 s42, s80
	s_mov_b32 s26, s42
	s_cbranch_scc0 .LBB0_2536
	s_and_b64 vcc, exec, s[16:17]
	s_cbranch_vccz .LBB0_2539
	s_barrier
